# nt hint extended: residual-epilogue x loads, final-phase output stores, prologue weight/w_ada loads
# baseline (speedup 1.0000x reference)
; __device__ __forceinline__ void phase_prologue(const Ctx& C) {
;     ...
;         const int kbeg = C.wave * 128;
; #pragma unroll 8
;         for (int k = kbeg; k < kbeg + 128; ++k) { const f32x4 w = *(const f32x4*)(wa + (size_t)k * NMOD);
; #pragma unroll
;             for (int b = 0; b < 8; ++b) acc[b] += w * sc[b * DM + k]; }
.LBB0_12:
	v_lshl_add_u64 v[40:41], v[38:39], 0, s[0:1]
	v_add_co_u32_e32 v42, vcc, s3, v40
	global_load_dwordx4 v[46:49], v[40:41], off nt
	s_nop 0
	v_addc_co_u32_e32 v43, vcc, 0, v41, vcc
	v_add_co_u32_e32 v114, vcc, s11, v40
	v_mov_b32_e32 v35, s10
	s_nop 0
	v_addc_co_u32_e32 v115, vcc, 0, v41, vcc
	v_add_co_u32_e32 v118, vcc, s12, v40
	ds_read_b128 v[50:53], v35
	ds_read_b128 v[54:57], v35 offset:16
	ds_read_b128 v[58:61], v35 offset:4096
	ds_read_b128 v[62:65], v35 offset:4112
	ds_read_b128 v[66:69], v35 offset:8192
	ds_read_b128 v[70:73], v35 offset:8208
	ds_read_b128 v[74:77], v35 offset:12288
	ds_read_b128 v[78:81], v35 offset:12304
	ds_read_b128 v[82:85], v35 offset:16384
	ds_read_b128 v[86:89], v35 offset:16400
	ds_read_b128 v[90:93], v35 offset:20480
	ds_read_b128 v[94:97], v35 offset:20496
	ds_read_b128 v[98:101], v35 offset:24576
	ds_read_b128 v[102:105], v35 offset:24592
	ds_read_b128 v[106:109], v35 offset:28672
	ds_read_b128 v[110:113], v35 offset:28688
	v_addc_co_u32_e32 v119, vcc, 0, v41, vcc
	v_add_co_u32_e32 v122, vcc, s13, v40
	s_waitcnt lgkmcnt(14)
	v_mov_b32_e32 v138, v53
	v_addc_co_u32_e32 v123, vcc, 0, v41, vcc
	v_add_co_u32_e32 v126, vcc, s14, v40
	s_waitcnt lgkmcnt(13)
	v_mov_b32_e32 v140, v61
	v_addc_co_u32_e32 v127, vcc, 0, v41, vcc
	v_add_co_u32_e32 v130, vcc, s15, v40
	s_waitcnt lgkmcnt(11)
	v_mov_b32_e32 v142, v69
	v_addc_co_u32_e32 v131, vcc, 0, v41, vcc
	v_add_co_u32_e32 v134, vcc, s16, v40
	s_waitcnt lgkmcnt(9)
	v_mov_b32_e32 v144, v77
	v_addc_co_u32_e32 v135, vcc, 0, v41, vcc
	global_load_dwordx4 v[40:43], v[42:43], off nt
	s_nop 0
	global_load_dwordx4 v[114:117], v[114:115], off nt
	s_nop 0
	global_load_dwordx4 v[118:121], v[118:119], off nt
	s_nop 0
	global_load_dwordx4 v[122:125], v[122:123], off nt
	s_nop 0
	global_load_dwordx4 v[126:129], v[126:127], off nt
	s_nop 0
	global_load_dwordx4 v[130:133], v[130:131], off nt
	s_nop 0
	global_load_dwordx4 v[134:137], v[134:135], off nt
	s_waitcnt lgkmcnt(7)
	v_mov_b32_e32 v146, v85
	s_waitcnt lgkmcnt(5)
	v_mov_b32_e32 v148, v93
	s_waitcnt lgkmcnt(3)
	v_mov_b32_e32 v150, v101
	s_waitcnt lgkmcnt(1)
	v_mov_b32_e32 v152, v109
	s_add_u32 s0, s0, 0x30000
	s_addc_u32 s1, s1, 0
	s_add_i32 s10, s10, 32
	v_mov_b32_e32 v154, v57
	v_mov_b32_e32 v156, v65
	v_mov_b32_e32 v158, v73
	v_mov_b32_e32 v160, v81
	v_mov_b32_e32 v164, v89
	v_mov_b32_e32 v166, v97
	v_mov_b32_e32 v168, v105
	s_waitcnt lgkmcnt(0)
	v_mov_b32_e32 v170, v113
	s_cmp_eq_u32 s0, 0x300000
	s_waitcnt vmcnt(7)
	v_pk_fma_f32 v[8:9], v[48:49], v[50:51], v[8:9] op_sel_hi:[1,0,1]
	v_pk_fma_f32 v[6:7], v[46:47], v[50:51], v[6:7] op_sel_hi:[1,0,1]
	v_pk_fma_f32 v[12:13], v[48:49], v[58:59], v[12:13] op_sel_hi:[1,0,1]
	v_pk_fma_f32 v[10:11], v[46:47], v[58:59], v[10:11] op_sel_hi:[1,0,1]
	v_pk_fma_f32 v[16:17], v[48:49], v[66:67], v[16:17] op_sel_hi:[1,0,1]
	v_pk_fma_f32 v[14:15], v[46:47], v[66:67], v[14:15] op_sel_hi:[1,0,1]
	v_pk_fma_f32 v[20:21], v[48:49], v[74:75], v[20:21] op_sel_hi:[1,0,1]
	v_pk_fma_f32 v[18:19], v[46:47], v[74:75], v[18:19] op_sel_hi:[1,0,1]
	v_pk_fma_f32 v[24:25], v[48:49], v[82:83], v[24:25] op_sel_hi:[1,0,1]
	v_pk_fma_f32 v[22:23], v[46:47], v[82:83], v[22:23] op_sel_hi:[1,0,1]
	v_pk_fma_f32 v[28:29], v[48:49], v[90:91], v[28:29] op_sel_hi:[1,0,1]
	v_pk_fma_f32 v[26:27], v[46:47], v[90:91], v[26:27] op_sel_hi:[1,0,1]
	v_pk_fma_f32 v[32:33], v[48:49], v[98:99], v[32:33] op_sel_hi:[1,0,1]
	v_pk_fma_f32 v[30:31], v[46:47], v[98:99], v[30:31] op_sel_hi:[1,0,1]
	v_pk_fma_f32 v[4:5], v[48:49], v[106:107], v[4:5] op_sel_hi:[1,0,1]
	v_pk_fma_f32 v[2:3], v[46:47], v[106:107], v[2:3] op_sel_hi:[1,0,1]
	s_waitcnt vmcnt(6)
	v_pk_fma_f32 v[6:7], v[40:41], v[50:51], v[6:7] op_sel:[0,1,0]
	v_pk_fma_f32 v[8:9], v[42:43], v[50:51], v[8:9] op_sel:[0,1,0]
	v_pk_fma_f32 v[10:11], v[40:41], v[58:59], v[10:11] op_sel:[0,1,0]
	v_pk_fma_f32 v[12:13], v[42:43], v[58:59], v[12:13] op_sel:[0,1,0]
	v_pk_fma_f32 v[14:15], v[40:41], v[66:67], v[14:15] op_sel:[0,1,0]
	v_pk_fma_f32 v[16:17], v[42:43], v[66:67], v[16:17] op_sel:[0,1,0]
	v_pk_fma_f32 v[18:19], v[40:41], v[74:75], v[18:19] op_sel:[0,1,0]
	v_pk_fma_f32 v[20:21], v[42:43], v[74:75], v[20:21] op_sel:[0,1,0]
	v_pk_fma_f32 v[22:23], v[40:41], v[82:83], v[22:23] op_sel:[0,1,0]
	v_pk_fma_f32 v[24:25], v[42:43], v[82:83], v[24:25] op_sel:[0,1,0]
	v_pk_fma_f32 v[26:27], v[40:41], v[90:91], v[26:27] op_sel:[0,1,0]
	v_pk_fma_f32 v[28:29], v[42:43], v[90:91], v[28:29] op_sel:[0,1,0]
	v_pk_fma_f32 v[30:31], v[40:41], v[98:99], v[30:31] op_sel:[0,1,0]
	v_pk_fma_f32 v[32:33], v[42:43], v[98:99], v[32:33] op_sel:[0,1,0]
	v_pk_fma_f32 v[2:3], v[40:41], v[106:107], v[2:3] op_sel:[0,1,0]
	v_pk_fma_f32 v[4:5], v[42:43], v[106:107], v[4:5] op_sel:[0,1,0]
	s_waitcnt vmcnt(5)
	v_pk_fma_f32 v[8:9], v[116:117], v[52:53], v[8:9] op_sel_hi:[1,0,1]
	v_pk_fma_f32 v[6:7], v[114:115], v[52:53], v[6:7] op_sel_hi:[1,0,1]
	v_pk_fma_f32 v[12:13], v[116:117], v[60:61], v[12:13] op_sel_hi:[1,0,1]
	v_pk_fma_f32 v[10:11], v[114:115], v[60:61], v[10:11] op_sel_hi:[1,0,1]
	v_pk_fma_f32 v[16:17], v[116:117], v[68:69], v[16:17] op_sel_hi:[1,0,1]
	v_pk_fma_f32 v[14:15], v[114:115], v[68:69], v[14:15] op_sel_hi:[1,0,1]
	v_pk_fma_f32 v[20:21], v[116:117], v[76:77], v[20:21] op_sel_hi:[1,0,1]
	v_pk_fma_f32 v[18:19], v[114:115], v[76:77], v[18:19] op_sel_hi:[1,0,1]
	v_pk_fma_f32 v[24:25], v[116:117], v[84:85], v[24:25] op_sel_hi:[1,0,1]
	v_pk_fma_f32 v[22:23], v[114:115], v[84:85], v[22:23] op_sel_hi:[1,0,1]
	v_pk_fma_f32 v[28:29], v[116:117], v[92:93], v[28:29] op_sel_hi:[1,0,1]
	v_pk_fma_f32 v[26:27], v[114:115], v[92:93], v[26:27] op_sel_hi:[1,0,1]
	v_pk_fma_f32 v[32:33], v[116:117], v[100:101], v[32:33] op_sel_hi:[1,0,1]
	v_pk_fma_f32 v[30:31], v[114:115], v[100:101], v[30:31] op_sel_hi:[1,0,1]
	v_pk_fma_f32 v[4:5], v[116:117], v[108:109], v[4:5] op_sel_hi:[1,0,1]
	v_pk_fma_f32 v[2:3], v[114:115], v[108:109], v[2:3] op_sel_hi:[1,0,1]
	s_waitcnt vmcnt(4)
; __device__ __forceinline__ void phase_prologue(const Ctx& C) {
;     ...
; #pragma unroll 8
;         for (int k = kbeg; k < kbeg + 128; ++k) { const f32x4 w = *(const f32x4*)(wa + (size_t)k * NMOD);
; #pragma unroll
;             for (int b = 0; b < 8; ++b) acc[b] += w * sc[b * DM + k]; }
	v_pk_fma_f32 v[8:9], v[120:121], v[138:139], v[8:9] op_sel_hi:[1,0,1]
	v_pk_fma_f32 v[6:7], v[118:119], v[138:139], v[6:7] op_sel_hi:[1,0,1]
	v_pk_fma_f32 v[12:13], v[120:121], v[140:141], v[12:13] op_sel_hi:[1,0,1]
	v_pk_fma_f32 v[10:11], v[118:119], v[140:141], v[10:11] op_sel_hi:[1,0,1]
	v_pk_fma_f32 v[16:17], v[120:121], v[142:143], v[16:17] op_sel_hi:[1,0,1]
	v_pk_fma_f32 v[14:15], v[118:119], v[142:143], v[14:15] op_sel_hi:[1,0,1]
	v_pk_fma_f32 v[20:21], v[120:121], v[144:145], v[20:21] op_sel_hi:[1,0,1]
	v_pk_fma_f32 v[18:19], v[118:119], v[144:145], v[18:19] op_sel_hi:[1,0,1]
	v_pk_fma_f32 v[24:25], v[120:121], v[146:147], v[24:25] op_sel_hi:[1,0,1]
	v_pk_fma_f32 v[22:23], v[118:119], v[146:147], v[22:23] op_sel_hi:[1,0,1]
	v_pk_fma_f32 v[28:29], v[120:121], v[148:149], v[28:29] op_sel_hi:[1,0,1]
	v_pk_fma_f32 v[26:27], v[118:119], v[148:149], v[26:27] op_sel_hi:[1,0,1]
	v_pk_fma_f32 v[32:33], v[120:121], v[150:151], v[32:33] op_sel_hi:[1,0,1]
	v_pk_fma_f32 v[30:31], v[118:119], v[150:151], v[30:31] op_sel_hi:[1,0,1]
	v_pk_fma_f32 v[4:5], v[120:121], v[152:153], v[4:5] op_sel_hi:[1,0,1]
	v_pk_fma_f32 v[2:3], v[118:119], v[152:153], v[2:3] op_sel_hi:[1,0,1]
	s_waitcnt vmcnt(3)
	v_pk_fma_f32 v[8:9], v[124:125], v[54:55], v[8:9] op_sel_hi:[1,0,1]
	v_pk_fma_f32 v[6:7], v[122:123], v[54:55], v[6:7] op_sel_hi:[1,0,1]
	v_pk_fma_f32 v[12:13], v[124:125], v[62:63], v[12:13] op_sel_hi:[1,0,1]
	v_pk_fma_f32 v[10:11], v[122:123], v[62:63], v[10:11] op_sel_hi:[1,0,1]
	v_pk_fma_f32 v[16:17], v[124:125], v[70:71], v[16:17] op_sel_hi:[1,0,1]
	v_pk_fma_f32 v[14:15], v[122:123], v[70:71], v[14:15] op_sel_hi:[1,0,1]
	v_pk_fma_f32 v[20:21], v[124:125], v[78:79], v[20:21] op_sel_hi:[1,0,1]
	v_pk_fma_f32 v[18:19], v[122:123], v[78:79], v[18:19] op_sel_hi:[1,0,1]
	v_pk_fma_f32 v[24:25], v[124:125], v[86:87], v[24:25] op_sel_hi:[1,0,1]
	v_pk_fma_f32 v[22:23], v[122:123], v[86:87], v[22:23] op_sel_hi:[1,0,1]
	v_pk_fma_f32 v[28:29], v[124:125], v[94:95], v[28:29] op_sel_hi:[1,0,1]
	v_pk_fma_f32 v[26:27], v[122:123], v[94:95], v[26:27] op_sel_hi:[1,0,1]
	v_pk_fma_f32 v[32:33], v[124:125], v[102:103], v[32:33] op_sel_hi:[1,0,1]
	v_pk_fma_f32 v[30:31], v[122:123], v[102:103], v[30:31] op_sel_hi:[1,0,1]
	v_pk_fma_f32 v[4:5], v[124:125], v[110:111], v[4:5] op_sel_hi:[1,0,1]
	v_pk_fma_f32 v[2:3], v[122:123], v[110:111], v[2:3] op_sel_hi:[1,0,1]
	s_waitcnt vmcnt(2)
	v_pk_fma_f32 v[8:9], v[128:129], v[54:55], v[8:9] op_sel:[0,1,0]
	v_pk_fma_f32 v[6:7], v[126:127], v[54:55], v[6:7] op_sel:[0,1,0]
	v_pk_fma_f32 v[12:13], v[128:129], v[62:63], v[12:13] op_sel:[0,1,0]
	v_pk_fma_f32 v[10:11], v[126:127], v[62:63], v[10:11] op_sel:[0,1,0]
	v_pk_fma_f32 v[16:17], v[128:129], v[70:71], v[16:17] op_sel:[0,1,0]
	v_pk_fma_f32 v[14:15], v[126:127], v[70:71], v[14:15] op_sel:[0,1,0]
	v_pk_fma_f32 v[20:21], v[128:129], v[78:79], v[20:21] op_sel:[0,1,0]
	v_pk_fma_f32 v[18:19], v[126:127], v[78:79], v[18:19] op_sel:[0,1,0]
	v_pk_fma_f32 v[24:25], v[128:129], v[86:87], v[24:25] op_sel:[0,1,0]
	v_pk_fma_f32 v[22:23], v[126:127], v[86:87], v[22:23] op_sel:[0,1,0]
	v_pk_fma_f32 v[28:29], v[128:129], v[94:95], v[28:29] op_sel:[0,1,0]
	v_pk_fma_f32 v[26:27], v[126:127], v[94:95], v[26:27] op_sel:[0,1,0]
	v_pk_fma_f32 v[32:33], v[128:129], v[102:103], v[32:33] op_sel:[0,1,0]
	v_pk_fma_f32 v[30:31], v[126:127], v[102:103], v[30:31] op_sel:[0,1,0]
	v_pk_fma_f32 v[4:5], v[128:129], v[110:111], v[4:5] op_sel:[0,1,0]
	v_pk_fma_f32 v[2:3], v[126:127], v[110:111], v[2:3] op_sel:[0,1,0]
	s_waitcnt vmcnt(1)
	v_pk_fma_f32 v[8:9], v[132:133], v[56:57], v[8:9] op_sel_hi:[1,0,1]
	v_pk_fma_f32 v[6:7], v[130:131], v[56:57], v[6:7] op_sel_hi:[1,0,1]
	v_pk_fma_f32 v[12:13], v[132:133], v[64:65], v[12:13] op_sel_hi:[1,0,1]
	v_pk_fma_f32 v[10:11], v[130:131], v[64:65], v[10:11] op_sel_hi:[1,0,1]
	v_pk_fma_f32 v[16:17], v[132:133], v[72:73], v[16:17] op_sel_hi:[1,0,1]
	v_pk_fma_f32 v[14:15], v[130:131], v[72:73], v[14:15] op_sel_hi:[1,0,1]
	v_pk_fma_f32 v[20:21], v[132:133], v[80:81], v[20:21] op_sel_hi:[1,0,1]
	v_pk_fma_f32 v[18:19], v[130:131], v[80:81], v[18:19] op_sel_hi:[1,0,1]
	v_pk_fma_f32 v[24:25], v[132:133], v[88:89], v[24:25] op_sel_hi:[1,0,1]
	v_pk_fma_f32 v[22:23], v[130:131], v[88:89], v[22:23] op_sel_hi:[1,0,1]
	v_pk_fma_f32 v[28:29], v[132:133], v[96:97], v[28:29] op_sel_hi:[1,0,1]
	v_pk_fma_f32 v[26:27], v[130:131], v[96:97], v[26:27] op_sel_hi:[1,0,1]
	v_pk_fma_f32 v[32:33], v[132:133], v[104:105], v[32:33] op_sel_hi:[1,0,1]
	v_pk_fma_f32 v[30:31], v[130:131], v[104:105], v[30:31] op_sel_hi:[1,0,1]
	v_pk_fma_f32 v[4:5], v[132:133], v[112:113], v[4:5] op_sel_hi:[1,0,1]
	v_pk_fma_f32 v[2:3], v[130:131], v[112:113], v[2:3] op_sel_hi:[1,0,1]
	s_waitcnt vmcnt(0)
	v_pk_fma_f32 v[8:9], v[136:137], v[154:155], v[8:9] op_sel_hi:[1,0,1]
	v_pk_fma_f32 v[6:7], v[134:135], v[154:155], v[6:7] op_sel_hi:[1,0,1]
	v_pk_fma_f32 v[12:13], v[136:137], v[156:157], v[12:13] op_sel_hi:[1,0,1]
	v_pk_fma_f32 v[10:11], v[134:135], v[156:157], v[10:11] op_sel_hi:[1,0,1]
	v_pk_fma_f32 v[16:17], v[136:137], v[158:159], v[16:17] op_sel_hi:[1,0,1]
	v_pk_fma_f32 v[14:15], v[134:135], v[158:159], v[14:15] op_sel_hi:[1,0,1]
	v_pk_fma_f32 v[20:21], v[136:137], v[160:161], v[20:21] op_sel_hi:[1,0,1]
	v_pk_fma_f32 v[18:19], v[134:135], v[160:161], v[18:19] op_sel_hi:[1,0,1]
	v_pk_fma_f32 v[24:25], v[136:137], v[164:165], v[24:25] op_sel_hi:[1,0,1]
	v_pk_fma_f32 v[22:23], v[134:135], v[164:165], v[22:23] op_sel_hi:[1,0,1]
	v_pk_fma_f32 v[28:29], v[136:137], v[166:167], v[28:29] op_sel_hi:[1,0,1]
	v_pk_fma_f32 v[26:27], v[134:135], v[166:167], v[26:27] op_sel_hi:[1,0,1]
	v_pk_fma_f32 v[32:33], v[136:137], v[168:169], v[32:33] op_sel_hi:[1,0,1]
	v_pk_fma_f32 v[30:31], v[134:135], v[168:169], v[30:31] op_sel_hi:[1,0,1]
	v_pk_fma_f32 v[4:5], v[136:137], v[170:171], v[4:5] op_sel_hi:[1,0,1]
	v_pk_fma_f32 v[2:3], v[134:135], v[170:171], v[2:3] op_sel_hi:[1,0,1]
	s_cbranch_scc0 .LBB0_12
; #define LAS __attribute__((address_space(3)))
; __device__ __forceinline__ void phase_prologue(const Ctx& C) {
;     ...
; #pragma unroll
;         for (int b = 0; b < 8; ++b) *(LAS f32x4*)(red + (C.wave * 8 + b) * 256 + lane * 4) = acc[b];
;         __syncthreads();
;         { const int b = C.wave; f32x4 s = *(const f32x4*)(C.in[3] + (size_t)l * NMOD + n0);
; #pragma unroll
;           for (int w = 0; w < 8; ++w) s += *(LAS f32x4*)(red + (w * 8 + b) * 256 + lane * 4);
;           *(f32x4*)((float*)(ws_ + WS_MOD) + ((size_t)l * BATCH + b) * NMOD + n0) = s; }
	v_readlane_b32 s3, v254, 20
	s_lshl_b32 s0, s3, 13
	s_add_i32 s0, s0, 0
	v_lshlrev_b32_e32 v1, 2, v1
	v_readlane_b32 s64, v254, 4
	v_add_u32_e32 v35, s0, v1
	s_mul_i32 s0, s2, 0x6000
	v_readlane_b32 s70, v254, 10
	s_mul_hi_u32 s1, s2, 0x6000
	v_readlane_b32 s71, v254, 11
	s_add_u32 s0, s70, s0
	s_addc_u32 s1, s71, s1
	v_lshlrev_b64 v[40:41], 2, v[36:37]
	ds_write_b128 v35, v[6:9] offset:32768
	ds_write_b128 v35, v[10:13] offset:33792
	ds_write_b128 v35, v[14:17] offset:34816
	ds_write_b128 v35, v[18:21] offset:35840
	ds_write_b128 v35, v[22:25] offset:36864
	ds_write_b128 v35, v[26:29] offset:37888
	ds_write_b128 v35, v[30:33] offset:38912
	ds_write_b128 v35, v[2:5] offset:39936
	v_lshl_add_u64 v[2:3], s[0:1], 0, v[40:41]
	s_waitcnt lgkmcnt(0)
	s_barrier
	global_load_dwordx4 v[2:5], v[2:3], off nt
	s_lshl_b32 s0, s3, 10
	s_add_i32 s0, s0, 0
	v_add_u32_e32 v1, s0, v1
	ds_read_b128 v[6:9], v1 offset:32768
	ds_read_b128 v[10:13], v1 offset:40960
	ds_read_b128 v[14:17], v1 offset:49152
	ds_read_b128 v[18:21], v1 offset:57344
	s_lshl_b32 s1, s2, 3
	s_add_i32 s1, s1, s3
	v_add_u32_e32 v35, 0x8000, v1
	s_mul_hi_u32 s2, s1, 0x6000
	s_mulk_i32 s1, 0x6000
	ds_read_b128 v[22:25], v35 offset:32768
	ds_read_b128 v[26:29], v35 offset:40960
	ds_read_b128 v[30:33], v35 offset:49152
	ds_read_b128 v[36:39], v35 offset:57344
	s_add_u32 s0, s4, s1
	s_addc_u32 s1, s5, s2
	v_lshl_add_u64 v[40:41], s[0:1], 0, v[40:41]
	v_add_co_u32_e32 v40, vcc, 0x10000, v40
	v_readlane_b32 s65, v254, 5
	s_nop 0
	v_addc_co_u32_e32 v41, vcc, 0, v41, vcc
	v_readlane_b32 s66, v254, 6
	v_readlane_b32 s67, v254, 7
	v_readlane_b32 s68, v254, 8
	v_readlane_b32 s69, v254, 9
	v_readlane_b32 s72, v254, 12
	v_readlane_b32 s73, v254, 13
	v_readlane_b32 s74, v254, 14
	v_readlane_b32 s75, v254, 15
	v_readlane_b32 s76, v254, 16
	v_readlane_b32 s77, v254, 17
	v_readlane_b32 s78, v254, 18
	v_readlane_b32 s79, v254, 19
	s_waitcnt vmcnt(0) lgkmcnt(7)
	v_pk_add_f32 v[4:5], v[4:5], v[8:9]
	v_pk_add_f32 v[2:3], v[2:3], v[6:7]
	s_waitcnt lgkmcnt(6)
	v_pk_add_f32 v[4:5], v[4:5], v[12:13]
	v_pk_add_f32 v[2:3], v[2:3], v[10:11]
	s_waitcnt lgkmcnt(5)
	v_pk_add_f32 v[4:5], v[4:5], v[16:17]
	v_pk_add_f32 v[2:3], v[2:3], v[14:15]
	s_waitcnt lgkmcnt(4)
	v_pk_add_f32 v[4:5], v[4:5], v[20:21]
	v_pk_add_f32 v[2:3], v[2:3], v[18:19]
	s_waitcnt lgkmcnt(3)
	v_pk_add_f32 v[4:5], v[4:5], v[24:25]
	v_pk_add_f32 v[2:3], v[2:3], v[22:23]
	s_waitcnt lgkmcnt(2)
	v_pk_add_f32 v[4:5], v[4:5], v[28:29]
	v_pk_add_f32 v[2:3], v[2:3], v[26:27]
	s_waitcnt lgkmcnt(1)
	v_pk_add_f32 v[4:5], v[4:5], v[32:33]
	v_pk_add_f32 v[2:3], v[2:3], v[30:31]
	s_waitcnt lgkmcnt(0)
	v_pk_add_f32 v[4:5], v[4:5], v[38:39]
	v_pk_add_f32 v[2:3], v[2:3], v[36:37]
	flat_store_dwordx4 v[40:41], v[2:5]
	s_waitcnt lgkmcnt(0)
	s_barrier

; #define LAS __attribute__((address_space(3)))
; __device__ __forceinline__ unsigned pk2(float lo, float hi) { return pg8::cvt_pk_bf16(lo, hi); }
; __device__ __forceinline__ void transpose_item(const float* W, int K, int N, bf16* WT, int row_off, LAS float* scr, int kb, int nb, int lane, const float* kscale = nullptr) {
;     const int k0 = 64 * kb, n0 = 32 * nb;
;     f32x4 v[8];
; #pragma unroll
;     for (int i = 0; i < 8; ++i) { v[i] = *(const f32x4*)(W + (size_t)(k0 + 8 * i + (lane >> 3)) * N + n0 + 4 * (lane & 7)); if (kscale) v[i] = v[i] * kscale[8 * i + (lane >> 3)]; }
; #pragma unroll
;     for (int i = 0; i < 8; ++i) { LAS float* d = scr + (8 * i + (lane >> 3)) * 33 + 4 * (lane & 7); d[0] = v[i].x; d[1] = v[i].y; d[2] = v[i].z; d[3] = v[i].w; }
;     asm volatile("s_waitcnt lgkmcnt(0)" ::: "memory");
;     const int c = lane & 7;
; #pragma unroll
;     for (int j = 0; j < 4; ++j) { const int n = (lane >> 3) + 8 * j; const LAS float* s = scr + (8 * c) * 33 + n;
;         u32x4 o; o.x = pk2(s[0 * 33], s[1 * 33]); o.y = pk2(s[2 * 33], s[3 * 33]); o.z = pk2(s[4 * 33], s[5 * 33]); o.w = pk2(s[6 * 33], s[7 * 33]);
;         *(u32x4*)(WT + (size_t)(row_off + n0 + n) * K + k0 + 8 * c) = o; }
;     asm volatile("s_waitcnt lgkmcnt(0)" ::: "memory");
; __device__ __forceinline__ void phase_prologue(const Ctx& C) {
;     ...
;         if (r < I_IN) { const int kb = r / 96, nb = r % 96, seg = nb >> 4;
;             const int nseg = (seg == 2) ? 4 : (seg == 3) ? 2 : (seg == 4) ? 3 : seg;
;             transpose_item(C.in[4] + (size_t)l * DM * W_IN, DM, W_IN, (bf16*)((unsigned char*)wl + WO_IN), (nseg - seg) * 512, scr, kb, nb, lane); continue; }
.LBB0_19:
	v_readlane_b32 s64, v254, 4
	s_mul_i32 s4, s26, 0xc00000
	v_readlane_b32 s72, v254, 12
	s_sext_i32_i16 s2, s42
	s_mul_hi_i32 s3, s26, 0xc00000
	v_readlane_b32 s73, v254, 13
	s_add_u32 s42, s72, s4
	s_addc_u32 s3, s73, s3
	s_sub_i32 s4, s41, s27
	s_lshl_b32 s41, s4, 9
	s_lshl_b32 s4, s0, 5
	s_ashr_i32 s5, s4, 31
	s_lshl_b32 s2, s2, 6
	s_lshl_b64 s[26:27], s[4:5], 2
	s_add_u32 s26, s42, s26
	v_add_u32_e32 v32, s2, v34
	s_addc_u32 s27, s3, s27
	v_lshl_add_u64 v[30:31], s[26:27], 0, v[36:37]
	v_add_u32_e32 v4, 8, v32
	v_add_u32_e32 v10, 16, v32
	v_add_u32_e32 v12, 24, v32
	v_add_u32_e32 v18, 32, v32
	v_add_u32_e32 v20, 40, v32
	v_mad_i64_i32 v[2:3], s[26:27], v32, s38, v[30:31]
	v_mad_i64_i32 v[6:7], s[26:27], v4, s38, v[30:31]
	v_mad_i64_i32 v[10:11], s[26:27], v10, s38, v[30:31]
	v_mad_i64_i32 v[14:15], s[26:27], v12, s38, v[30:31]
	v_mad_i64_i32 v[18:19], s[26:27], v18, s38, v[30:31]
	v_mad_i64_i32 v[22:23], s[26:27], v20, s38, v[30:31]
	global_load_dwordx4 v[2:5], v[2:3], off nt
	s_nop 0
	global_load_dwordx4 v[6:9], v[6:7], off nt
	s_nop 0
	global_load_dwordx4 v[10:13], v[10:11], off nt
	s_nop 0
	global_load_dwordx4 v[14:17], v[14:15], off nt
	s_nop 0
	global_load_dwordx4 v[18:21], v[18:19], off nt
	s_nop 0
	global_load_dwordx4 v[22:25], v[22:23], off nt
	v_add_u32_e32 v26, 48, v32
	v_mad_i64_i32 v[26:27], s[26:27], v26, s38, v[30:31]
	global_load_dwordx4 v[26:29], v[26:27], off nt
	v_add_u32_e32 v32, 56, v32
	v_mad_i64_i32 v[30:31], s[26:27], v32, s38, v[30:31]
	global_load_dwordx4 v[30:33], v[30:31], off nt
	s_ashr_i32 s3, s2, 31
	s_add_i32 s41, s41, s4
	s_lshl_b64 s[2:3], s[2:3], 1
	v_add_u32_e32 v40, s41, v34
	s_add_u32 s2, s40, s2
	v_mov_b32_e32 v39, v37
	v_ashrrev_i32_e32 v41, 31, v40
	s_addc_u32 s3, s39, s3
	v_lshlrev_b64 v[40:41], 11, v[40:41]
	v_lshl_add_u64 v[64:65], s[2:3], 0, v[38:39]
	v_add_u32_e32 v62, s41, v1
	v_ashrrev_i32_e32 v63, 31, v62
	v_lshlrev_b64 v[62:63], 11, v[62:63]
	v_readlane_b32 s65, v254, 5
	v_readlane_b32 s66, v254, 6
	v_readlane_b32 s67, v254, 7
	v_readlane_b32 s68, v254, 8
	v_readlane_b32 s69, v254, 9
	v_readlane_b32 s70, v254, 10
	v_readlane_b32 s71, v254, 11
	v_readlane_b32 s74, v254, 14
	v_readlane_b32 s75, v254, 15
	v_readlane_b32 s76, v254, 16
	v_readlane_b32 s77, v254, 17
	v_readlane_b32 s78, v254, 18
	v_readlane_b32 s79, v254, 19
	s_waitcnt vmcnt(0)
	ds_write2_b32 v45, v2, v3 offset1:1
	ds_write2_b32 v45, v4, v5 offset0:2 offset1:3
	ds_write2_b32 v46, v6, v7 offset1:1
	ds_write2_b32 v47, v8, v9 offset1:1
	ds_write2_b32 v48, v10, v11 offset1:1
	ds_write2_b32 v49, v12, v13 offset1:1
	ds_write2_b32 v50, v14, v15 offset1:1
	ds_write2_b32 v51, v16, v17 offset1:1
	ds_write2_b32 v52, v18, v19 offset1:1
	ds_write2_b32 v53, v20, v21 offset1:1
	ds_write2_b32 v54, v22, v23 offset1:1
	ds_write2_b32 v55, v24, v25 offset1:1
	ds_write2_b32 v56, v26, v27 offset1:1
	ds_write2_b32 v57, v28, v29 offset1:1
	ds_write2_b32 v58, v30, v31 offset1:1
	ds_write2_b32 v59, v32, v33 offset1:1
	s_waitcnt lgkmcnt(0)
	ds_read_b32 v2, v44
	ds_read_b32 v3, v44 offset:132
	ds_read_b32 v4, v44 offset:264
	ds_read_b32 v5, v44 offset:396
	ds_read_b32 v8, v44 offset:528
	ds_read_b32 v9, v44 offset:660
	ds_read_b32 v10, v44 offset:792
	ds_read_b32 v11, v44 offset:924
	v_lshl_add_u64 v[6:7], v[64:65], 0, v[40:41]
	s_waitcnt lgkmcnt(0)
	v_cvt_pk_bf16_f32 v2, v2, v3
	v_cvt_pk_bf16_f32 v3, v4, v5
	v_cvt_pk_bf16_f32 v4, v8, v9
	v_cvt_pk_bf16_f32 v5, v10, v11
	flat_store_dwordx4 v[6:7], v[2:5]
	ds_read_b32 v2, v44 offset:32
	ds_read_b32 v3, v44 offset:164
	ds_read_b32 v4, v44 offset:296
	ds_read_b32 v5, v44 offset:428
	ds_read_b32 v8, v44 offset:560
	ds_read_b32 v9, v44 offset:692
	ds_read_b32 v10, v44 offset:824
	ds_read_b32 v11, v44 offset:956
	v_lshl_add_u64 v[6:7], v[64:65], 0, v[62:63]
	s_waitcnt lgkmcnt(0)
	v_cvt_pk_bf16_f32 v2, v2, v3
	v_cvt_pk_bf16_f32 v3, v4, v5
	v_cvt_pk_bf16_f32 v4, v8, v9
	v_cvt_pk_bf16_f32 v5, v10, v11
	flat_store_dwordx4 v[6:7], v[2:5]
	ds_read_b32 v2, v44 offset:64
	ds_read_b32 v3, v44 offset:196
	ds_read_b32 v4, v44 offset:328
	ds_read_b32 v5, v44 offset:460
	ds_read_b32 v6, v44 offset:592
	ds_read_b32 v7, v44 offset:724
	ds_read_b32 v8, v44 offset:856
	ds_read_b32 v9, v44 offset:988
	s_waitcnt lgkmcnt(0)
	v_cvt_pk_bf16_f32 v2, v2, v3
	v_cvt_pk_bf16_f32 v3, v4, v5
	v_cvt_pk_bf16_f32 v4, v6, v7
	v_add_u32_e32 v6, s41, v42
	v_ashrrev_i32_e32 v7, 31, v6
	v_lshlrev_b64 v[6:7], 11, v[6:7]
	v_cvt_pk_bf16_f32 v5, v8, v9
	v_lshl_add_u64 v[6:7], v[64:65], 0, v[6:7]
	flat_store_dwordx4 v[6:7], v[2:5]
	ds_read_b32 v2, v44 offset:96
	ds_read_b32 v3, v44 offset:228
	ds_read_b32 v4, v44 offset:360
	ds_read_b32 v5, v44 offset:492
	ds_read_b32 v6, v44 offset:624
	ds_read_b32 v7, v44 offset:756
	ds_read_b32 v8, v44 offset:888
	ds_read_b32 v9, v44 offset:1020
	s_waitcnt lgkmcnt(0)
	v_cvt_pk_bf16_f32 v2, v2, v3
	v_cvt_pk_bf16_f32 v3, v4, v5
	v_cvt_pk_bf16_f32 v4, v6, v7
	v_add_u32_e32 v6, s41, v43
	v_ashrrev_i32_e32 v7, 31, v6
	v_lshlrev_b64 v[6:7], 11, v[6:7]
	v_cvt_pk_bf16_f32 v5, v8, v9
	v_lshl_add_u64 v[6:7], v[64:65], 0, v[6:7]
	flat_store_dwordx4 v[6:7], v[2:5]
	s_waitcnt lgkmcnt(0)

; #define LAS __attribute__((address_space(3)))
; __device__ __forceinline__ void transpose_item(const float* W, int K, int N, bf16* WT, int row_off, LAS float* scr, int kb, int nb, int lane, const float* kscale = nullptr) {
;     const int k0 = 64 * kb, n0 = 32 * nb;
;     f32x4 v[8];
; #pragma unroll
;     for (int i = 0; i < 8; ++i) { v[i] = *(const f32x4*)(W + (size_t)(k0 + 8 * i + (lane >> 3)) * N + n0 + 4 * (lane & 7)); if (kscale) v[i] = v[i] * kscale[8 * i + (lane >> 3)]; }
; #pragma unroll
;     for (int i = 0; i < 8; ++i) { LAS float* d = scr + (8 * i + (lane >> 3)) * 33 + 4 * (lane & 7); d[0] = v[i].x; d[1] = v[i].y; d[2] = v[i].z; d[3] = v[i].w; }
;     asm volatile("s_waitcnt lgkmcnt(0)" ::: "memory");
;     const int c = lane & 7;
; #pragma unroll
;     for (int j = 0; j < 4; ++j) { const int n = (lane >> 3) + 8 * j; const LAS float* s = scr + (8 * c) * 33 + n;
;         u32x4 o; o.x = pk2(s[0 * 33], s[1 * 33]); o.y = pk2(s[2 * 33], s[3 * 33]); o.z = pk2(s[4 * 33], s[5 * 33]); o.w = pk2(s[6 * 33], s[7 * 33]);
;         *(u32x4*)(WT + (size_t)(row_off + n0 + n) * K + k0 + 8 * c) = o; }
;     asm volatile("s_waitcnt lgkmcnt(0)" ::: "memory");
; __device__ __forceinline__ void phase_prologue(const Ctx& C) {
;     ...
;     for (int it = gw; it < DEPTH * I_L; it += NGW) {
;         const int l = it / I_L; int r = it % I_L;
;         bf16* wl = (bf16*)(ws_ + WS_W + (size_t)l * WS_WL);
;         if (r < I_IN) { const int kb = r / 96, nb = r % 96, seg = nb >> 4;
;             const int nseg = (seg == 2) ? 4 : (seg == 3) ? 2 : (seg == 4) ? 3 : seg;
;             transpose_item(C.in[4] + (size_t)l * DM * W_IN, DM, W_IN, (bf16*)((unsigned char*)wl + WO_IN), (nseg - seg) * 512, scr, kb, nb, lane); continue; }
;         r -= I_IN;
;         if (r < I_OUT) { const int kb = r / 32, k0 = 64 * kb;
;             transpose_item(C.in[8] + (size_t)l * DM * DM, DM, DM, (bf16*)((unsigned char*)wl + WO_OUT), 0, scr, kb, r % 32, lane, k0 < 512 ? C.in[6] + (size_t)l * 512 + k0 : C.in[7] + (size_t)l * 512 + (k0 - 512)); continue; }
;         r -= I_OUT;
;         if (r < I_UP) { const int kb = r / 176, nb = r % 176, n0 = 32 * nb, isv = n0 >= DFF ? 1 : 0, j0 = n0 - DFF * isv;
;             transpose_item(C.in[9] + (size_t)l * DM * NUP, DM, NUP, (bf16*)((unsigned char*)wl + WO_UP), 256 * (j0 >> 7) + 128 * isv + (j0 & 127) - n0, scr, kb, nb, lane); continue; }
;         r -= I_UP;
.LBB0_21:
	s_mul_hi_i32 s0, s16, 0x5397829d
	s_lshr_b32 s2, s0, 31
	s_ashr_i32 s0, s0, 11
	s_add_i32 s26, s0, s2
	s_mul_i32 s0, s26, 0xffffe780
	s_add_i32 s41, s16, s0
	s_ashr_i32 s27, s26, 31
	s_mul_i32 s2, s26, 0x1900000
	s_mul_hi_i32 s0, s26, 0x1900000
	s_add_u32 s40, s18, s2
	s_addc_u32 s39, s19, s0
	s_cmpk_gt_i32 s41, 0x5ff
	s_mov_b64 s[2:3], -1
	s_cbranch_scc0 .LBB0_47
	s_cmpk_gt_u32 s41, 0x7ff
	s_cbranch_scc0 .LBB0_28
	s_cmpk_gt_u32 s41, 0x12ff
	s_cbranch_scc0 .LBB0_25
	s_mul_i32 s2, s26, 0xb00000
	s_mul_hi_i32 s0, s26, 0xb00000
	s_add_u32 s3, s56, s2
	s_addc_u32 s5, s57, s0
	s_mul_i32 s0, s26, 0xffffcf00
	s_add_i32 s0, s22, s0
	s_and_b32 s0, s0, 0x7fffffc0
	s_and_b32 s2, s20, 0x3e0
	s_addk_i32 s0, 0xda00
	s_lshl_b32 s4, s2, 2
	v_add_u32_e32 v2, s0, v34
	s_add_u32 s4, s3, s4
	s_addc_u32 s5, s5, 0
	v_ashrrev_i32_e32 v3, 31, v2
	v_lshl_add_u64 v[4:5], s[4:5], 0, v[36:37]
	v_lshlrev_b64 v[2:3], 12, v[2:3]
	v_lshl_add_u64 v[30:31], v[4:5], 0, v[2:3]
	v_add_co_u32_e32 v6, vcc, s28, v30
	s_lshl_b64 s[4:5], s[0:1], 1
	s_nop 0
	v_addc_co_u32_e32 v7, vcc, 0, v31, vcc
	v_add_co_u32_e32 v10, vcc, s29, v30
	global_load_dwordx4 v[2:5], v[30:31], off nt
	s_nop 0
	global_load_dwordx4 v[6:9], v[6:7], off nt
	v_addc_co_u32_e32 v11, vcc, 0, v31, vcc
	v_add_co_u32_e32 v14, vcc, s30, v30
	s_add_u32 s4, s40, s4
	s_nop 0
	v_addc_co_u32_e32 v15, vcc, 0, v31, vcc
	v_add_co_u32_e32 v18, vcc, s31, v30
	global_load_dwordx4 v[10:13], v[10:11], off nt
	s_nop 0
	global_load_dwordx4 v[14:17], v[14:15], off nt
	v_addc_co_u32_e32 v19, vcc, 0, v31, vcc
	v_add_co_u32_e32 v22, vcc, s33, v30
	v_mov_b32_e32 v39, v37
	s_nop 0
	v_addc_co_u32_e32 v23, vcc, 0, v31, vcc
	global_load_dwordx4 v[18:21], v[18:19], off nt
	s_nop 0
	global_load_dwordx4 v[22:25], v[22:23], off nt
	v_add_co_u32_e32 v26, vcc, s34, v30
	s_addc_u32 s5, s39, s5
	s_nop 0
	v_addc_co_u32_e32 v27, vcc, 0, v31, vcc
	global_load_dwordx4 v[26:29], v[26:27], off nt
	v_add_co_u32_e32 v30, vcc, s35, v30
	v_lshl_add_u64 v[40:41], s[4:5], 0, v[38:39]
	s_nop 0
	v_addc_co_u32_e32 v31, vcc, 0, v31, vcc
	global_load_dwordx4 v[30:33], v[30:31], off nt
	v_add_u32_e32 v61, s2, v34
	v_lshl_add_u64 v[40:41], v[40:41], 0, s[10:11]
	s_waitcnt vmcnt(0)
	ds_write2_b32 v45, v2, v3 offset1:1
	ds_write2_b32 v45, v4, v5 offset0:2 offset1:3
	ds_write2_b32 v46, v6, v7 offset1:1
	ds_write2_b32 v47, v8, v9 offset1:1
	ds_write2_b32 v48, v10, v11 offset1:1
	ds_write2_b32 v49, v12, v13 offset1:1
	ds_write2_b32 v50, v14, v15 offset1:1
	ds_write2_b32 v51, v16, v17 offset1:1
	ds_write2_b32 v52, v18, v19 offset1:1
	ds_write2_b32 v53, v20, v21 offset1:1
	ds_write2_b32 v54, v22, v23 offset1:1
	ds_write2_b32 v55, v24, v25 offset1:1
	ds_write2_b32 v56, v26, v27 offset1:1
	ds_write2_b32 v57, v28, v29 offset1:1
	ds_write2_b32 v58, v30, v31 offset1:1
	ds_write2_b32 v59, v32, v33 offset1:1
	s_waitcnt lgkmcnt(0)
	ds_read_b32 v2, v44
	ds_read_b32 v3, v44 offset:132
	ds_read_b32 v4, v44 offset:264
	ds_read_b32 v5, v44 offset:396
	ds_read_b32 v8, v44 offset:528
	ds_read_b32 v9, v44 offset:660
	ds_read_b32 v10, v44 offset:792
	ds_read_b32 v11, v44 offset:924
	v_mad_i64_i32 v[6:7], s[4:5], v61, s36, v[40:41]
	s_waitcnt lgkmcnt(0)
	v_cvt_pk_bf16_f32 v2, v2, v3
	v_cvt_pk_bf16_f32 v3, v4, v5
	v_cvt_pk_bf16_f32 v4, v8, v9
	v_cvt_pk_bf16_f32 v5, v10, v11
	flat_store_dwordx4 v[6:7], v[2:5]
	ds_read_b32 v2, v44 offset:32
	ds_read_b32 v3, v44 offset:164
	ds_read_b32 v4, v44 offset:296
	ds_read_b32 v5, v44 offset:428
	ds_read_b32 v6, v44 offset:560
	ds_read_b32 v7, v44 offset:692
	ds_read_b32 v8, v44 offset:824
	ds_read_b32 v9, v44 offset:956
	v_add_u32_e32 v10, s2, v1
	s_waitcnt lgkmcnt(0)
	v_cvt_pk_bf16_f32 v2, v2, v3
	v_cvt_pk_bf16_f32 v3, v4, v5
	v_cvt_pk_bf16_f32 v4, v6, v7
	v_cvt_pk_bf16_f32 v5, v8, v9
	v_mad_i64_i32 v[6:7], s[4:5], v10, s36, v[40:41]
	flat_store_dwordx4 v[6:7], v[2:5]
	ds_read_b32 v2, v44 offset:64
	ds_read_b32 v3, v44 offset:196
	ds_read_b32 v4, v44 offset:328
	ds_read_b32 v5, v44 offset:460
	ds_read_b32 v6, v44 offset:592
	ds_read_b32 v7, v44 offset:724
	ds_read_b32 v8, v44 offset:856
	ds_read_b32 v9, v44 offset:988
	s_waitcnt lgkmcnt(0)
	v_cvt_pk_bf16_f32 v2, v2, v3
	v_cvt_pk_bf16_f32 v3, v4, v5
	v_cvt_pk_bf16_f32 v4, v6, v7
	v_add_u32_e32 v6, s2, v42
	v_cvt_pk_bf16_f32 v5, v8, v9
	v_mad_i64_i32 v[6:7], s[4:5], v6, s36, v[40:41]
	flat_store_dwordx4 v[6:7], v[2:5]
	ds_read_b32 v2, v44 offset:96
	ds_read_b32 v3, v44 offset:228
	ds_read_b32 v4, v44 offset:360
	ds_read_b32 v5, v44 offset:492
	ds_read_b32 v6, v44 offset:624
	ds_read_b32 v7, v44 offset:756
	ds_read_b32 v8, v44 offset:888
	ds_read_b32 v9, v44 offset:1020
	s_waitcnt lgkmcnt(0)
	v_cvt_pk_bf16_f32 v2, v2, v3
	v_cvt_pk_bf16_f32 v3, v4, v5
	v_cvt_pk_bf16_f32 v4, v6, v7
	v_add_u32_e32 v6, s2, v43
	v_cvt_pk_bf16_f32 v5, v8, v9
	v_mad_i64_i32 v[6:7], s[2:3], v6, s36, v[40:41]
	flat_store_dwordx4 v[6:7], v[2:5]
	s_waitcnt lgkmcnt(0)
	s_mov_b64 s[2:3], 0
; #define LAS __attribute__((address_space(3)))
; __device__ __forceinline__ unsigned pk2(float lo, float hi) { return pg8::cvt_pk_bf16(lo, hi); }
; __device__ __forceinline__ void transpose_item(const float* W, int K, int N, bf16* WT, int row_off, LAS float* scr, int kb, int nb, int lane, const float* kscale = nullptr) {
;     const int k0 = 64 * kb, n0 = 32 * nb;
;     f32x4 v[8];
; #pragma unroll
;     for (int i = 0; i < 8; ++i) { v[i] = *(const f32x4*)(W + (size_t)(k0 + 8 * i + (lane >> 3)) * N + n0 + 4 * (lane & 7)); if (kscale) v[i] = v[i] * kscale[8 * i + (lane >> 3)]; }
; #pragma unroll
;     for (int i = 0; i < 8; ++i) { LAS float* d = scr + (8 * i + (lane >> 3)) * 33 + 4 * (lane & 7); d[0] = v[i].x; d[1] = v[i].y; d[2] = v[i].z; d[3] = v[i].w; }
;     asm volatile("s_waitcnt lgkmcnt(0)" ::: "memory");
;     const int c = lane & 7;
; #pragma unroll
;     for (int j = 0; j < 4; ++j) { const int n = (lane >> 3) + 8 * j; const LAS float* s = scr + (8 * c) * 33 + n;
;         u32x4 o; o.x = pk2(s[0 * 33], s[1 * 33]); o.y = pk2(s[2 * 33], s[3 * 33]); o.z = pk2(s[4 * 33], s[5 * 33]); o.w = pk2(s[6 * 33], s[7 * 33]);
;         *(u32x4*)(WT + (size_t)(row_off + n0 + n) * K + k0 + 8 * c) = o; }
;     asm volatile("s_waitcnt lgkmcnt(0)" ::: "memory");
; __device__ __forceinline__ void phase_prologue(const Ctx& C) {
;     ...
;         if (r < I_UP) { const int kb = r / 176, nb = r % 176, n0 = 32 * nb, isv = n0 >= DFF ? 1 : 0, j0 = n0 - DFF * isv;
;             transpose_item(C.in[9] + (size_t)l * DM * NUP, DM, NUP, (bf16*)((unsigned char*)wl + WO_UP), 256 * (j0 >> 7) + 128 * isv + (j0 & 127) - n0, scr, kb, nb, lane); continue; }
.LBB0_25:
	s_andn2_b64 vcc, exec, s[2:3]
	s_cbranch_vccnz .LBB0_27
	s_add_i32 s0, s41, 0xf800
	s_and_b32 s2, s0, 0xffff
	s_mul_i32 s2, s2, 0xba2f
	s_lshr_b32 s4, s2, 23
	s_mul_i32 s2, s4, 0xb0
	s_sub_i32 s0, s0, s2
	s_lshl_b32 s2, s0, 5
	s_and_b32 s3, s2, 0xffe0
	s_and_b32 s0, s0, 0xffff
	s_cmpk_gt_u32 s0, 0x57
	s_cselect_b32 s0, 0xfffff500, 0
	s_mul_i32 s42, s26, 0x1600000
	s_cselect_b32 s43, 0x80, 0
	s_add_i32 s0, s0, s3
	s_mul_hi_i32 s5, s26, 0x1600000
	s_add_u32 s42, s50, s42
	s_addc_u32 s5, s51, s5
	s_lshl_b32 s0, s0, 1
	s_and_b32 s2, s2, 0x60
	s_and_b32 s0, s0, 0xffffff00
	s_or_b32 s2, s2, s43
	s_or_b32 s0, s2, s0
	s_lshl_b32 s2, s3, 2
	s_add_u32 s2, s42, s2
	v_lshl_add_u32 v32, s4, 6, v34
	s_addc_u32 s3, s5, 0
	v_lshl_add_u64 v[30:31], s[2:3], 0, v[36:37]
	v_add_u32_e32 v4, 8, v32
	v_add_u32_e32 v10, 16, v32
	v_add_u32_e32 v12, 24, v32
	v_add_u32_e32 v18, 32, v32
	v_add_u32_e32 v20, 40, v32
	v_mad_i64_i32 v[2:3], s[2:3], v32, s37, v[30:31]
	v_mad_i64_i32 v[6:7], s[2:3], v4, s37, v[30:31]
	v_mad_i64_i32 v[10:11], s[2:3], v10, s37, v[30:31]
	v_mad_i64_i32 v[14:15], s[2:3], v12, s37, v[30:31]
	v_mad_i64_i32 v[18:19], s[2:3], v18, s37, v[30:31]
	v_mad_i64_i32 v[22:23], s[2:3], v20, s37, v[30:31]
	global_load_dwordx4 v[2:5], v[2:3], off nt
	s_nop 0
	global_load_dwordx4 v[6:9], v[6:7], off nt
	s_nop 0
	global_load_dwordx4 v[10:13], v[10:11], off nt
	s_nop 0
	global_load_dwordx4 v[14:17], v[14:15], off nt
	s_nop 0
	global_load_dwordx4 v[18:21], v[18:19], off nt
	s_nop 0
	global_load_dwordx4 v[22:25], v[22:23], off nt
	v_add_u32_e32 v26, 48, v32
	v_mad_i64_i32 v[26:27], s[2:3], v26, s37, v[30:31]
	global_load_dwordx4 v[26:29], v[26:27], off nt
	v_add_u32_e32 v32, 56, v32
	v_mad_i64_i32 v[30:31], s[2:3], v32, s37, v[30:31]
	global_load_dwordx4 v[30:33], v[30:31], off nt
	s_lshl_b32 s2, s4, 7
	s_add_u32 s2, s40, s2
	v_mov_b32_e32 v39, v37
	v_add_u32_e32 v40, s0, v34
	s_addc_u32 s3, s39, 0
	v_ashrrev_i32_e32 v41, 31, v40
	v_lshl_add_u64 v[64:65], s[2:3], 0, v[38:39]
	v_lshlrev_b64 v[40:41], 11, v[40:41]
	v_lshl_add_u64 v[64:65], v[64:65], 0, s[12:13]
	v_add_u32_e32 v62, s0, v1
	v_ashrrev_i32_e32 v63, 31, v62
	v_lshlrev_b64 v[62:63], 11, v[62:63]
	s_waitcnt vmcnt(0)
	ds_write2_b32 v45, v2, v3 offset1:1
	ds_write2_b32 v45, v4, v5 offset0:2 offset1:3
	ds_write2_b32 v46, v6, v7 offset1:1
	ds_write2_b32 v47, v8, v9 offset1:1
	ds_write2_b32 v48, v10, v11 offset1:1
	ds_write2_b32 v49, v12, v13 offset1:1
	ds_write2_b32 v50, v14, v15 offset1:1
	ds_write2_b32 v51, v16, v17 offset1:1
	ds_write2_b32 v52, v18, v19 offset1:1
	ds_write2_b32 v53, v20, v21 offset1:1
	ds_write2_b32 v54, v22, v23 offset1:1
	ds_write2_b32 v55, v24, v25 offset1:1
	ds_write2_b32 v56, v26, v27 offset1:1
	ds_write2_b32 v57, v28, v29 offset1:1
	ds_write2_b32 v58, v30, v31 offset1:1
	ds_write2_b32 v59, v32, v33 offset1:1
	s_waitcnt lgkmcnt(0)
	ds_read_b32 v2, v44
	ds_read_b32 v3, v44 offset:132
	ds_read_b32 v4, v44 offset:264
	ds_read_b32 v5, v44 offset:396
	ds_read_b32 v8, v44 offset:528
	ds_read_b32 v9, v44 offset:660
	ds_read_b32 v10, v44 offset:792
	ds_read_b32 v11, v44 offset:924
	v_lshl_add_u64 v[6:7], v[64:65], 0, v[40:41]
	s_waitcnt lgkmcnt(0)
	v_cvt_pk_bf16_f32 v2, v2, v3
	v_cvt_pk_bf16_f32 v3, v4, v5
	v_cvt_pk_bf16_f32 v4, v8, v9
	v_cvt_pk_bf16_f32 v5, v10, v11
	flat_store_dwordx4 v[6:7], v[2:5]
	ds_read_b32 v2, v44 offset:32
	ds_read_b32 v3, v44 offset:164
	ds_read_b32 v4, v44 offset:296
	ds_read_b32 v5, v44 offset:428
	ds_read_b32 v8, v44 offset:560
	ds_read_b32 v9, v44 offset:692
	ds_read_b32 v10, v44 offset:824
	ds_read_b32 v11, v44 offset:956
	v_lshl_add_u64 v[6:7], v[64:65], 0, v[62:63]
	s_waitcnt lgkmcnt(0)
	v_cvt_pk_bf16_f32 v2, v2, v3
	v_cvt_pk_bf16_f32 v3, v4, v5
	v_cvt_pk_bf16_f32 v4, v8, v9
	v_cvt_pk_bf16_f32 v5, v10, v11
	flat_store_dwordx4 v[6:7], v[2:5]
	ds_read_b32 v2, v44 offset:64
	ds_read_b32 v3, v44 offset:196
	ds_read_b32 v4, v44 offset:328
	ds_read_b32 v5, v44 offset:460
	ds_read_b32 v6, v44 offset:592
	ds_read_b32 v7, v44 offset:724
	ds_read_b32 v8, v44 offset:856
	ds_read_b32 v9, v44 offset:988
	s_waitcnt lgkmcnt(0)
	v_cvt_pk_bf16_f32 v2, v2, v3
	v_cvt_pk_bf16_f32 v3, v4, v5
	v_cvt_pk_bf16_f32 v4, v6, v7
	v_add_u32_e32 v6, s0, v42
	v_ashrrev_i32_e32 v7, 31, v6
	v_lshlrev_b64 v[6:7], 11, v[6:7]
	v_cvt_pk_bf16_f32 v5, v8, v9
	v_lshl_add_u64 v[6:7], v[64:65], 0, v[6:7]
	flat_store_dwordx4 v[6:7], v[2:5]
	ds_read_b32 v2, v44 offset:96
	ds_read_b32 v3, v44 offset:228
	ds_read_b32 v4, v44 offset:360
	ds_read_b32 v5, v44 offset:492
	ds_read_b32 v6, v44 offset:624
	ds_read_b32 v7, v44 offset:756
	ds_read_b32 v8, v44 offset:888
	ds_read_b32 v9, v44 offset:1020
	s_waitcnt lgkmcnt(0)
	v_cvt_pk_bf16_f32 v2, v2, v3
	v_cvt_pk_bf16_f32 v3, v4, v5
	v_cvt_pk_bf16_f32 v4, v6, v7
	v_add_u32_e32 v6, s0, v43
	v_ashrrev_i32_e32 v7, 31, v6
	v_lshlrev_b64 v[6:7], 11, v[6:7]
	v_cvt_pk_bf16_f32 v5, v8, v9
	v_lshl_add_u64 v[6:7], v[64:65], 0, v[6:7]
	flat_store_dwordx4 v[6:7], v[2:5]
	s_waitcnt lgkmcnt(0)

; #define LAS __attribute__((address_space(3)))
; __device__ __forceinline__ void transpose_item(const float* W, int K, int N, bf16* WT, int row_off, LAS float* scr, int kb, int nb, int lane, const float* kscale = nullptr) {
;     const int k0 = 64 * kb, n0 = 32 * nb;
;     f32x4 v[8];
; #pragma unroll
;     for (int i = 0; i < 8; ++i) { v[i] = *(const f32x4*)(W + (size_t)(k0 + 8 * i + (lane >> 3)) * N + n0 + 4 * (lane & 7)); if (kscale) v[i] = v[i] * kscale[8 * i + (lane >> 3)]; }
; #pragma unroll
;     for (int i = 0; i < 8; ++i) { LAS float* d = scr + (8 * i + (lane >> 3)) * 33 + 4 * (lane & 7); d[0] = v[i].x; d[1] = v[i].y; d[2] = v[i].z; d[3] = v[i].w; }
; __device__ __forceinline__ void phase_prologue(const Ctx& C) {
;     ...
;         if (r < I_OUT) { const int kb = r / 32, k0 = 64 * kb;
;             transpose_item(C.in[8] + (size_t)l * DM * DM, DM, DM, (bf16*)((unsigned char*)wl + WO_OUT), 0, scr, kb, r % 32, lane, k0 < 512 ? C.in[6] + (size_t)l * 512 + k0 : C.in[7] + (size_t)l * 512 + (k0 - 512)); continue; }
.LBB0_28:
	s_andn2_b64 vcc, exec, s[2:3]
	s_cbranch_vccnz .LBB0_46
	s_lshl_b32 s0, s26, 8
	s_sub_i32 s0, s22, s0
	s_and_b32 s0, s0, 0xfc0
	s_addk_i32 s0, 0xf400
	s_lshl_b64 s[2:3], s[26:27], 22
	s_add_u32 s42, s48, s2
	v_readlane_b32 s64, v254, 4
	s_addc_u32 s43, s49, s3
	s_lshl_b64 s[2:3], s[26:27], 11
	v_readlane_b32 s76, v254, 16
	v_readlane_b32 s77, v254, 17
	s_add_u32 s27, s76, s2
	s_addc_u32 s44, s77, s3
	s_lshl_b64 s[4:5], s[0:1], 2
	s_add_u32 s27, s27, s4
	v_readlane_b32 s78, v254, 18
	s_addc_u32 s44, s44, s5
	v_readlane_b32 s79, v254, 19
	s_add_u32 s2, s78, s2
	s_addc_u32 s3, s79, s3
	s_add_u32 s2, s2, s4
	s_addc_u32 s3, s3, s5
	s_add_u32 s2, s2, 0xfffff800
	s_addc_u32 s3, s3, -1
	s_cmpk_lt_u32 s0, 0x200
	s_cselect_b32 s5, s44, s3
	s_cselect_b32 s4, s27, s2
	s_and_b32 s27, s20, 0x3e0
	s_lshl_b32 s2, s27, 2
	v_add_u32_e32 v26, s0, v34
	s_add_u32 s2, s42, s2
	s_addc_u32 s3, s43, 0
	v_ashrrev_i32_e32 v27, 31, v26
	v_lshl_add_u64 v[28:29], s[2:3], 0, v[36:37]
	v_lshlrev_b64 v[2:3], 12, v[26:27]
	v_lshl_add_u64 v[6:7], v[28:29], 0, v[2:3]
	global_load_dwordx4 v[2:5], v[6:7], off nt
	s_cmp_lg_u64 s[4:5], 0
	s_cselect_b64 s[2:3], -1, 0
	s_cmp_eq_u64 s[4:5], 0
	v_lshl_add_u64 v[40:41], v[34:35], 2, s[4:5]
	v_readlane_b32 s65, v254, 5
	v_readlane_b32 s66, v254, 6
	v_readlane_b32 s67, v254, 7
	v_readlane_b32 s68, v254, 8
	v_readlane_b32 s69, v254, 9
	v_readlane_b32 s70, v254, 10
	v_readlane_b32 s71, v254, 11
	v_readlane_b32 s72, v254, 12
	v_readlane_b32 s73, v254, 13
	v_readlane_b32 s74, v254, 14
	v_readlane_b32 s75, v254, 15
	s_cbranch_scc1 .LBB0_31
	global_load_dword v8, v[40:41], off
	s_waitcnt vmcnt(0)
	v_pk_mul_f32 v[4:5], v[4:5], v[8:9] op_sel_hi:[1,0]
	v_pk_mul_f32 v[2:3], v[2:3], v[8:9] op_sel_hi:[1,0]
.LBB0_31:
	v_add_co_u32_e32 v6, vcc, 0x8000, v6
	v_cndmask_b32_e64 v10, 0, 1, s[2:3]
	s_nop 0
	v_addc_co_u32_e32 v7, vcc, 0, v7, vcc
	global_load_dwordx4 v[6:9], v[6:7], off nt
	v_cmp_ne_u32_e64 s[4:5], 1, v10
	s_andn2_b64 vcc, exec, s[2:3]
	s_cbranch_vccnz .LBB0_33
	global_load_dword v10, v[40:41], off offset:32
	s_waitcnt vmcnt(0)
	v_pk_mul_f32 v[8:9], v[8:9], v[10:11] op_sel_hi:[1,0]
	v_pk_mul_f32 v[6:7], v[6:7], v[10:11] op_sel_hi:[1,0]
.LBB0_33:
	v_lshlrev_b64 v[10:11], 12, v[26:27]
	v_lshl_add_u64 v[14:15], v[28:29], 0, v[10:11]
	v_add_co_u32_e32 v10, vcc, 0x10000, v14
	s_nop 1
	v_addc_co_u32_e32 v11, vcc, 0, v15, vcc
	global_load_dwordx4 v[10:13], v[10:11], off nt
	s_and_b64 vcc, exec, s[4:5]
	s_cbranch_vccnz .LBB0_35
	global_load_dword v16, v[40:41], off offset:64
	s_waitcnt vmcnt(0)
	v_pk_mul_f32 v[12:13], v[12:13], v[16:17] op_sel_hi:[1,0]
	v_pk_mul_f32 v[10:11], v[10:11], v[16:17] op_sel_hi:[1,0]
.LBB0_35:
	v_add_co_u32_e32 v14, vcc, 0x18000, v14
	s_nop 1
	v_addc_co_u32_e32 v15, vcc, 0, v15, vcc
	global_load_dwordx4 v[14:17], v[14:15], off nt
	s_and_b64 vcc, exec, s[4:5]
	s_cbranch_vccnz .LBB0_37
	global_load_dword v18, v[40:41], off offset:96
	s_waitcnt vmcnt(0)
	v_pk_mul_f32 v[16:17], v[16:17], v[18:19] op_sel_hi:[1,0]
	v_pk_mul_f32 v[14:15], v[14:15], v[18:19] op_sel_hi:[1,0]
.LBB0_37:
	v_lshlrev_b64 v[18:19], 12, v[26:27]
	v_lshl_add_u64 v[22:23], v[28:29], 0, v[18:19]
	v_add_co_u32_e32 v18, vcc, 0x20000, v22
	s_nop 1
	v_addc_co_u32_e32 v19, vcc, 0, v23, vcc
	global_load_dwordx4 v[18:21], v[18:19], off nt
	s_and_b64 vcc, exec, s[4:5]
	s_cbranch_vccnz .LBB0_39
	global_load_dword v24, v[40:41], off offset:128
	s_waitcnt vmcnt(0)
	v_pk_mul_f32 v[20:21], v[20:21], v[24:25] op_sel_hi:[1,0]
	v_pk_mul_f32 v[18:19], v[18:19], v[24:25] op_sel_hi:[1,0]
.LBB0_39:
	v_add_co_u32_e32 v22, vcc, 0x28000, v22
	s_nop 1
	v_addc_co_u32_e32 v23, vcc, 0, v23, vcc
	global_load_dwordx4 v[22:25], v[22:23], off nt
	s_and_b64 vcc, exec, s[4:5]
	s_cbranch_vccnz .LBB0_41
	global_load_dword v30, v[40:41], off offset:160
	s_waitcnt vmcnt(0)
	v_pk_mul_f32 v[24:25], v[24:25], v[30:31] op_sel_hi:[1,0]
	v_pk_mul_f32 v[22:23], v[22:23], v[30:31] op_sel_hi:[1,0]
.LBB0_41:
	v_lshlrev_b64 v[26:27], 12, v[26:27]
	v_lshl_add_u64 v[30:31], v[28:29], 0, v[26:27]
	v_add_co_u32_e32 v26, vcc, 0x30000, v30
	s_nop 1
	v_addc_co_u32_e32 v27, vcc, 0, v31, vcc
	global_load_dwordx4 v[26:29], v[26:27], off nt
	s_and_b64 vcc, exec, s[4:5]
	s_cbranch_vccnz .LBB0_43
	global_load_dword v32, v[40:41], off offset:192
	s_waitcnt vmcnt(0)
	v_pk_mul_f32 v[28:29], v[28:29], v[32:33] op_sel_hi:[1,0]
	v_pk_mul_f32 v[26:27], v[26:27], v[32:33] op_sel_hi:[1,0]
.LBB0_43:
	v_add_co_u32_e32 v30, vcc, 0x38000, v30
	s_nop 1
	v_addc_co_u32_e32 v31, vcc, 0, v31, vcc
	global_load_dwordx4 v[30:33], v[30:31], off nt
	s_and_b64 vcc, exec, s[4:5]
	s_cbranch_vccnz .LBB0_45
	global_load_dword v40, v[40:41], off offset:224
	s_waitcnt vmcnt(0)
	v_pk_mul_f32 v[32:33], v[32:33], v[40:41] op_sel_hi:[1,0]
	v_pk_mul_f32 v[30:31], v[30:31], v[40:41] op_sel_hi:[1,0]

;     __device__ __forceinline__ void load_x(f32x4 (&x)[2][2], size_t off) const {
; #pragma unroll
;         for (int bj = 0; bj < 2; ++bj) {
;             if constexpr (XIN_F32) { x[bj][0] = *(const f32x4*)((const float*)xin + off + bj * HALF); x[bj][1] = *(const f32x4*)((const float*)xin + off + bj * HALF + 4); }
;             else { const u32x4 w = *(const u32x4*)((const bf16_t*)xin + off + bj * HALF);
;                 x[bj][0] = (f32x4){__builtin_bit_cast(float, w.x << 16), __builtin_bit_cast(float, w.x & 0xffff0000u), __builtin_bit_cast(float, w.y << 16), __builtin_bit_cast(float, w.y & 0xffff0000u)};
;                 x[bj][1] = (f32x4){__builtin_bit_cast(float, w.z << 16), __builtin_bit_cast(float, w.z & 0xffff0000u), __builtin_bit_cast(float, w.w << 16), __builtin_bit_cast(float, w.w & 0xffff0000u)}; } }
;     }
;     __device__ __forceinline__ void operator()(const f32x4 (&acc)[2][2][4][2], const Unit& u, int wr, int wc, int fr, int fq) const {
;         const int row0 = u.pm * BM + wr * 64 + fr; const int col0 = u.pn * BM + wc * 32 + 8 * fq;
;         const int b = (u.pm * BM) >> 12;
;         f32x4 gv[2][2];
; #pragma unroll
;         for (int bj = 0; bj < 2; ++bj)
; #pragma unroll
;             for (int n = 0; n < 2; ++n) gv[bj][n] = *(const f32x4*)(gate + (size_t)b * gate_ld + col0 + bj * HALF + n * 4);
;         f32x4 xv[2][2][2];
;         load_x(xv[0], (size_t)row0 * 1024 + col0);
; #pragma unroll
;         for (int g = 0; g < 8; ++g) { const int ai = g >> 2, m = g & 3; const size_t off = (size_t)(row0 + ai * HALF + m * 16) * 1024 + col0;
;             if (g + 1 < 8) { const int ai2 = (g + 1) >> 2, m2 = (g + 1) & 3; load_x(xv[(g + 1) & 1], (size_t)(row0 + ai2 * HALF + m2 * 16) * 1024 + col0); }
;             float rs_ = 1.0f; if constexpr (ROWSCALE) rs_ = tab[((u.pm == pm0 ? 0 : 256) + ai * HALF + wr * 64 + m * 16 + fr) * 2 + 1];
; #pragma unroll
;             for (int bj = 0; bj < 2; ++bj) { const f32x4 v0 = xv[g & 1][bj][0] + gv[bj][0] * (acc[ai][bj][m][0] * rs_), v1 = xv[g & 1][bj][1] + gv[bj][1] * (acc[ai][bj][m][1] * rs_);
;                 u32x4 w; w.x = cvt_pk_bf16(v0[0], v0[1]); w.y = cvt_pk_bf16(v0[2], v0[3]); w.z = cvt_pk_bf16(v1[0], v1[1]); w.w = cvt_pk_bf16(v1[2], v1[3]);
;                 *(u32x4*)(out + off + bj * HALF) = w; } }
.LBB0_417:
	v_lshl_or_b32 v221, s5, 8, v203
	s_ashr_i32 s3, s4, 4
	s_mul_hi_i32 s5, s3, 0x6000
	s_mulk_i32 s3, 0x6000
	s_add_u32 s12, s64, s3
	s_addc_u32 s13, s65, s5
	v_lshlrev_b32_e32 v223, 2, v221
	global_load_dwordx4 v[60:63], v223, s[12:13]
	global_load_dwordx4 v[56:59], v223, s[12:13] offset:16
	global_load_dwordx4 v[52:55], v223, s[12:13] offset:512
	global_load_dwordx4 v[48:51], v223, s[12:13] offset:528
	v_lshlrev_b32_e32 v213, 11, v198
	v_lshl_add_u32 v213, v221, 1, v213
	s_lshl_b32 s3, s4, 19
	s_add_u32 s98, s38, s3
	s_addc_u32 s99, s39, 0
	s_mov_b64 s[100:101], s[98:99]
	v_readlane_b32 s3, v255, 49
	s_nop 0
	s_cmp_eq_u32 s4, s3
	s_cselect_b32 s4, 0, 0x100
	v_add_u32_e32 v80, s4, v198
	s_add_i32 s5, 0, 0x22800
	v_lshl_add_u32 v80, v80, 3, s5
	s_mov_b32 s3, 0x40000
	s_mov_b64 s[12:13], 0x40000
	s_mov_b32 s78, s1
	global_load_dwordx4 v[176:179], v213, s[98:99] nt
	global_load_dwordx4 v[180:183], v213, s[98:99] offset:256 nt
	s_add_u32 s98, s98, 0x8000
	s_addc_u32 s99, s99, 0
	global_load_dwordx4 v[184:187], v213, s[98:99] nt
	global_load_dwordx4 v[188:191], v213, s[98:99] offset:256 nt
	s_add_u32 s98, s98, 0x8000
	s_addc_u32 s99, s99, 0
	global_load_dwordx4 v[192:195], v213, s[98:99] nt
	global_load_dwordx4 v[224:227], v213, s[98:99] offset:256 nt
	s_add_u32 s98, s98, 0x8000
	s_addc_u32 s99, s99, 0
	global_load_dwordx4 v[232:235], v213, s[98:99] nt
	global_load_dwordx4 v[236:239], v213, s[98:99] offset:256 nt
	s_add_u32 s98, s98, 0x28000
	s_addc_u32 s99, s99, 0
	global_load_dwordx4 v[240:243], v213, s[98:99] nt
	global_load_dwordx4 v[244:247], v213, s[98:99] offset:256 nt
	s_add_u32 s98, s98, 0x8000
	s_addc_u32 s99, s99, 0
	ds_read_b32 v212, v80 offset:4
	ds_read_b32 v220, v80 offset:132
	ds_read_b32 v222, v80 offset:260
	ds_read_b32 v228, v80 offset:388
	ds_read_b32 v230, v80 offset:1028
	ds_read_b32 v248, v80 offset:1156
	ds_read_b32 v250, v80 offset:1284
	ds_read_b32 v82, v80 offset:1412
	s_waitcnt lgkmcnt(0)
	s_waitcnt vmcnt(8)
	v_pk_mul_f32 v[144:145], v[144:145], v[212:213] op_sel_hi:[1,0]
	v_pk_mul_f32 v[146:147], v[146:147], v[212:213] op_sel_hi:[1,0]
	v_pk_mul_f32 v[140:141], v[140:141], v[212:213] op_sel_hi:[1,0]
	v_pk_mul_f32 v[142:143], v[142:143], v[212:213] op_sel_hi:[1,0]
	v_lshlrev_b32_e32 v160, 16, v176
	v_and_b32_e32 v161, 0xffff0000, v176
	v_lshlrev_b32_e32 v174, 16, v177
	v_and_b32_e32 v175, 0xffff0000, v177
	v_lshlrev_b32_e32 v196, 16, v178
	v_and_b32_e32 v197, 0xffff0000, v178
	v_lshlrev_b32_e32 v210, 16, v179
	v_and_b32_e32 v211, 0xffff0000, v179
	v_pk_fma_f32 v[144:145], v[60:61], v[144:145], v[160:161]
	v_pk_fma_f32 v[146:147], v[62:63], v[146:147], v[174:175]
	v_pk_fma_f32 v[140:141], v[56:57], v[140:141], v[196:197]
	v_pk_fma_f32 v[142:143], v[58:59], v[142:143], v[210:211]
	v_cvt_pk_bf16_f32 v176, v144, v145
	v_cvt_pk_bf16_f32 v177, v146, v147
	v_cvt_pk_bf16_f32 v178, v140, v141
	v_cvt_pk_bf16_f32 v179, v142, v143
	global_store_dwordx4 v213, v[176:179], s[100:101]
	v_pk_mul_f32 v[136:137], v[136:137], v[212:213] op_sel_hi:[1,0]
	v_pk_mul_f32 v[138:139], v[138:139], v[212:213] op_sel_hi:[1,0]
	v_pk_mul_f32 v[132:133], v[132:133], v[212:213] op_sel_hi:[1,0]
	v_pk_mul_f32 v[134:135], v[134:135], v[212:213] op_sel_hi:[1,0]
	v_lshlrev_b32_e32 v160, 16, v180
	v_and_b32_e32 v161, 0xffff0000, v180
	v_lshlrev_b32_e32 v174, 16, v181
	v_and_b32_e32 v175, 0xffff0000, v181
	v_lshlrev_b32_e32 v196, 16, v182
	v_and_b32_e32 v197, 0xffff0000, v182
	v_lshlrev_b32_e32 v210, 16, v183
	v_and_b32_e32 v211, 0xffff0000, v183
	v_pk_fma_f32 v[136:137], v[52:53], v[136:137], v[160:161]
	v_pk_fma_f32 v[138:139], v[54:55], v[138:139], v[174:175]
	v_pk_fma_f32 v[132:133], v[48:49], v[132:133], v[196:197]
	v_pk_fma_f32 v[134:135], v[50:51], v[134:135], v[210:211]
	v_cvt_pk_bf16_f32 v180, v136, v137
	v_cvt_pk_bf16_f32 v181, v138, v139
	v_cvt_pk_bf16_f32 v182, v132, v133
	v_cvt_pk_bf16_f32 v183, v134, v135
	global_store_dwordx4 v213, v[180:183], s[100:101] offset:256
	s_add_u32 s100, s100, 0x8000
	s_addc_u32 s101, s101, 0
	global_load_dwordx4 v[176:179], v213, s[98:99] nt
	global_load_dwordx4 v[180:183], v213, s[98:99] offset:256 nt
	s_add_u32 s98, s98, 0x8000
	s_addc_u32 s99, s99, 0
	s_waitcnt vmcnt(10)
	v_pk_mul_f32 v[128:129], v[128:129], v[220:221] op_sel_hi:[1,0]
	v_pk_mul_f32 v[130:131], v[130:131], v[220:221] op_sel_hi:[1,0]
	v_pk_mul_f32 v[124:125], v[124:125], v[220:221] op_sel_hi:[1,0]
	v_pk_mul_f32 v[126:127], v[126:127], v[220:221] op_sel_hi:[1,0]
	v_lshlrev_b32_e32 v160, 16, v184
	v_and_b32_e32 v161, 0xffff0000, v184
	v_lshlrev_b32_e32 v174, 16, v185
	v_and_b32_e32 v175, 0xffff0000, v185
	v_lshlrev_b32_e32 v196, 16, v186
	v_and_b32_e32 v197, 0xffff0000, v186
	v_lshlrev_b32_e32 v210, 16, v187
	v_and_b32_e32 v211, 0xffff0000, v187
	v_pk_fma_f32 v[128:129], v[60:61], v[128:129], v[160:161]
	v_pk_fma_f32 v[130:131], v[62:63], v[130:131], v[174:175]
	v_pk_fma_f32 v[124:125], v[56:57], v[124:125], v[196:197]
	v_pk_fma_f32 v[126:127], v[58:59], v[126:127], v[210:211]
	v_cvt_pk_bf16_f32 v184, v128, v129
	v_cvt_pk_bf16_f32 v185, v130, v131
	v_cvt_pk_bf16_f32 v186, v124, v125
	v_cvt_pk_bf16_f32 v187, v126, v127
	global_store_dwordx4 v213, v[184:187], s[100:101]
	v_pk_mul_f32 v[120:121], v[120:121], v[220:221] op_sel_hi:[1,0]
	v_pk_mul_f32 v[122:123], v[122:123], v[220:221] op_sel_hi:[1,0]
	v_pk_mul_f32 v[116:117], v[116:117], v[220:221] op_sel_hi:[1,0]
	v_pk_mul_f32 v[118:119], v[118:119], v[220:221] op_sel_hi:[1,0]
	v_lshlrev_b32_e32 v160, 16, v188
	v_and_b32_e32 v161, 0xffff0000, v188
	v_lshlrev_b32_e32 v174, 16, v189
	v_and_b32_e32 v175, 0xffff0000, v189
	v_lshlrev_b32_e32 v196, 16, v190
	v_and_b32_e32 v197, 0xffff0000, v190
	v_lshlrev_b32_e32 v210, 16, v191
	v_and_b32_e32 v211, 0xffff0000, v191
	v_pk_fma_f32 v[120:121], v[52:53], v[120:121], v[160:161]
	v_pk_fma_f32 v[122:123], v[54:55], v[122:123], v[174:175]
	v_pk_fma_f32 v[116:117], v[48:49], v[116:117], v[196:197]
	v_pk_fma_f32 v[118:119], v[50:51], v[118:119], v[210:211]
	v_cvt_pk_bf16_f32 v188, v120, v121
	v_cvt_pk_bf16_f32 v189, v122, v123
	v_cvt_pk_bf16_f32 v190, v116, v117
	v_cvt_pk_bf16_f32 v191, v118, v119
	global_store_dwordx4 v213, v[188:191], s[100:101] offset:256
	s_add_u32 s100, s100, 0x8000
	s_addc_u32 s101, s101, 0
	global_load_dwordx4 v[184:187], v213, s[98:99] nt
	global_load_dwordx4 v[188:191], v213, s[98:99] offset:256 nt
	s_add_u32 s98, s98, 0x8000
	s_addc_u32 s99, s99, 0
	s_waitcnt vmcnt(12)
;     __device__ __forceinline__ void load_x(f32x4 (&x)[2][2], size_t off) const {
; #pragma unroll
;         for (int bj = 0; bj < 2; ++bj) {
;             if constexpr (XIN_F32) { x[bj][0] = *(const f32x4*)((const float*)xin + off + bj * HALF); x[bj][1] = *(const f32x4*)((const float*)xin + off + bj * HALF + 4); }
;             else { const u32x4 w = *(const u32x4*)((const bf16_t*)xin + off + bj * HALF);
;                 x[bj][0] = (f32x4){__builtin_bit_cast(float, w.x << 16), __builtin_bit_cast(float, w.x & 0xffff0000u), __builtin_bit_cast(float, w.y << 16), __builtin_bit_cast(float, w.y & 0xffff0000u)};
;                 x[bj][1] = (f32x4){__builtin_bit_cast(float, w.z << 16), __builtin_bit_cast(float, w.z & 0xffff0000u), __builtin_bit_cast(float, w.w << 16), __builtin_bit_cast(float, w.w & 0xffff0000u)}; } }
;     }
;     __device__ __forceinline__ void operator()(const f32x4 (&acc)[2][2][4][2], const Unit& u, int wr, int wc, int fr, int fq) const {
;         const int row0 = u.pm * BM + wr * 64 + fr; const int col0 = u.pn * BM + wc * 32 + 8 * fq;
;         const int b = (u.pm * BM) >> 12;
;         f32x4 gv[2][2];
; #pragma unroll
;         for (int bj = 0; bj < 2; ++bj)
; #pragma unroll
;             for (int n = 0; n < 2; ++n) gv[bj][n] = *(const f32x4*)(gate + (size_t)b * gate_ld + col0 + bj * HALF + n * 4);
;         f32x4 xv[2][2][2];
;         load_x(xv[0], (size_t)row0 * 1024 + col0);
; #pragma unroll
;         for (int g = 0; g < 8; ++g) { const int ai = g >> 2, m = g & 3; const size_t off = (size_t)(row0 + ai * HALF + m * 16) * 1024 + col0;
;             if (g + 1 < 8) { const int ai2 = (g + 1) >> 2, m2 = (g + 1) & 3; load_x(xv[(g + 1) & 1], (size_t)(row0 + ai2 * HALF + m2 * 16) * 1024 + col0); }
;             float rs_ = 1.0f; if constexpr (ROWSCALE) rs_ = tab[((u.pm == pm0 ? 0 : 256) + ai * HALF + wr * 64 + m * 16 + fr) * 2 + 1];
; #pragma unroll
;             for (int bj = 0; bj < 2; ++bj) { const f32x4 v0 = xv[g & 1][bj][0] + gv[bj][0] * (acc[ai][bj][m][0] * rs_), v1 = xv[g & 1][bj][1] + gv[bj][1] * (acc[ai][bj][m][1] * rs_);
;                 u32x4 w; w.x = cvt_pk_bf16(v0[0], v0[1]); w.y = cvt_pk_bf16(v0[2], v0[3]); w.z = cvt_pk_bf16(v1[0], v1[1]); w.w = cvt_pk_bf16(v1[2], v1[3]);
;                 *(u32x4*)(out + off + bj * HALF) = w; } }
	v_pk_mul_f32 v[112:113], v[112:113], v[222:223] op_sel_hi:[1,0]
	v_pk_mul_f32 v[114:115], v[114:115], v[222:223] op_sel_hi:[1,0]
	v_pk_mul_f32 v[108:109], v[108:109], v[222:223] op_sel_hi:[1,0]
	v_pk_mul_f32 v[110:111], v[110:111], v[222:223] op_sel_hi:[1,0]
	v_lshlrev_b32_e32 v160, 16, v192
	v_and_b32_e32 v161, 0xffff0000, v192
	v_lshlrev_b32_e32 v174, 16, v193
	v_and_b32_e32 v175, 0xffff0000, v193
	v_lshlrev_b32_e32 v196, 16, v194
	v_and_b32_e32 v197, 0xffff0000, v194
	v_lshlrev_b32_e32 v210, 16, v195
	v_and_b32_e32 v211, 0xffff0000, v195
	v_pk_fma_f32 v[112:113], v[60:61], v[112:113], v[160:161]
	v_pk_fma_f32 v[114:115], v[62:63], v[114:115], v[174:175]
	v_pk_fma_f32 v[108:109], v[56:57], v[108:109], v[196:197]
	v_pk_fma_f32 v[110:111], v[58:59], v[110:111], v[210:211]
	v_cvt_pk_bf16_f32 v192, v112, v113
	v_cvt_pk_bf16_f32 v193, v114, v115
	v_cvt_pk_bf16_f32 v194, v108, v109
	v_cvt_pk_bf16_f32 v195, v110, v111
	global_store_dwordx4 v213, v[192:195], s[100:101]
	v_pk_mul_f32 v[104:105], v[104:105], v[222:223] op_sel_hi:[1,0]
	v_pk_mul_f32 v[106:107], v[106:107], v[222:223] op_sel_hi:[1,0]
	v_pk_mul_f32 v[100:101], v[100:101], v[222:223] op_sel_hi:[1,0]
	v_pk_mul_f32 v[102:103], v[102:103], v[222:223] op_sel_hi:[1,0]
	v_lshlrev_b32_e32 v160, 16, v224
	v_and_b32_e32 v161, 0xffff0000, v224
	v_lshlrev_b32_e32 v174, 16, v225
	v_and_b32_e32 v175, 0xffff0000, v225
	v_lshlrev_b32_e32 v196, 16, v226
	v_and_b32_e32 v197, 0xffff0000, v226
	v_lshlrev_b32_e32 v210, 16, v227
	v_and_b32_e32 v211, 0xffff0000, v227
	v_pk_fma_f32 v[104:105], v[52:53], v[104:105], v[160:161]
	v_pk_fma_f32 v[106:107], v[54:55], v[106:107], v[174:175]
	v_pk_fma_f32 v[100:101], v[48:49], v[100:101], v[196:197]
	v_pk_fma_f32 v[102:103], v[50:51], v[102:103], v[210:211]
	v_cvt_pk_bf16_f32 v224, v104, v105
	v_cvt_pk_bf16_f32 v225, v106, v107
	v_cvt_pk_bf16_f32 v226, v100, v101
	v_cvt_pk_bf16_f32 v227, v102, v103
	global_store_dwordx4 v213, v[224:227], s[100:101] offset:256
	s_add_u32 s100, s100, 0x8000
	s_addc_u32 s101, s101, 0
	global_load_dwordx4 v[192:195], v213, s[98:99] nt
	global_load_dwordx4 v[224:227], v213, s[98:99] offset:256 nt
	s_add_u32 s98, s98, 0x8000
	s_addc_u32 s99, s99, 0
	s_waitcnt vmcnt(14)
	v_pk_mul_f32 v[96:97], v[96:97], v[228:229] op_sel_hi:[1,0]
	v_pk_mul_f32 v[98:99], v[98:99], v[228:229] op_sel_hi:[1,0]
	v_pk_mul_f32 v[92:93], v[92:93], v[228:229] op_sel_hi:[1,0]
	v_pk_mul_f32 v[94:95], v[94:95], v[228:229] op_sel_hi:[1,0]
	v_lshlrev_b32_e32 v160, 16, v232
	v_and_b32_e32 v161, 0xffff0000, v232
	v_lshlrev_b32_e32 v174, 16, v233
	v_and_b32_e32 v175, 0xffff0000, v233
	v_lshlrev_b32_e32 v196, 16, v234
	v_and_b32_e32 v197, 0xffff0000, v234
	v_lshlrev_b32_e32 v210, 16, v235
	v_and_b32_e32 v211, 0xffff0000, v235
	v_pk_fma_f32 v[96:97], v[60:61], v[96:97], v[160:161]
	v_pk_fma_f32 v[98:99], v[62:63], v[98:99], v[174:175]
	v_pk_fma_f32 v[92:93], v[56:57], v[92:93], v[196:197]
	v_pk_fma_f32 v[94:95], v[58:59], v[94:95], v[210:211]
	v_cvt_pk_bf16_f32 v232, v96, v97
	v_cvt_pk_bf16_f32 v233, v98, v99
	v_cvt_pk_bf16_f32 v234, v92, v93
	v_cvt_pk_bf16_f32 v235, v94, v95
	global_store_dwordx4 v213, v[232:235], s[100:101]
	v_pk_mul_f32 v[88:89], v[88:89], v[228:229] op_sel_hi:[1,0]
	v_pk_mul_f32 v[90:91], v[90:91], v[228:229] op_sel_hi:[1,0]
	v_pk_mul_f32 v[84:85], v[84:85], v[228:229] op_sel_hi:[1,0]
	v_pk_mul_f32 v[86:87], v[86:87], v[228:229] op_sel_hi:[1,0]
	v_lshlrev_b32_e32 v160, 16, v236
	v_and_b32_e32 v161, 0xffff0000, v236
	v_lshlrev_b32_e32 v174, 16, v237
	v_and_b32_e32 v175, 0xffff0000, v237
	v_lshlrev_b32_e32 v196, 16, v238
	v_and_b32_e32 v197, 0xffff0000, v238
	v_lshlrev_b32_e32 v210, 16, v239
	v_and_b32_e32 v211, 0xffff0000, v239
	v_pk_fma_f32 v[88:89], v[52:53], v[88:89], v[160:161]
	v_pk_fma_f32 v[90:91], v[54:55], v[90:91], v[174:175]
	v_pk_fma_f32 v[84:85], v[48:49], v[84:85], v[196:197]
	v_pk_fma_f32 v[86:87], v[50:51], v[86:87], v[210:211]
	v_cvt_pk_bf16_f32 v236, v88, v89
	v_cvt_pk_bf16_f32 v237, v90, v91
	v_cvt_pk_bf16_f32 v238, v84, v85
	v_cvt_pk_bf16_f32 v239, v86, v87
	global_store_dwordx4 v213, v[236:239], s[100:101] offset:256
	s_add_u32 s100, s100, 0x28000
	s_addc_u32 s101, s101, 0
	s_waitcnt vmcnt(14)
	v_pk_mul_f32 v[76:77], v[76:77], v[230:231] op_sel_hi:[1,0]
	v_pk_mul_f32 v[78:79], v[78:79], v[230:231] op_sel_hi:[1,0]
	v_pk_mul_f32 v[72:73], v[72:73], v[230:231] op_sel_hi:[1,0]
	v_pk_mul_f32 v[74:75], v[74:75], v[230:231] op_sel_hi:[1,0]
	v_lshlrev_b32_e32 v160, 16, v240
	v_and_b32_e32 v161, 0xffff0000, v240
	v_lshlrev_b32_e32 v174, 16, v241
	v_and_b32_e32 v175, 0xffff0000, v241
	v_lshlrev_b32_e32 v196, 16, v242
	v_and_b32_e32 v197, 0xffff0000, v242
	v_lshlrev_b32_e32 v210, 16, v243
	v_and_b32_e32 v211, 0xffff0000, v243
	v_pk_fma_f32 v[76:77], v[60:61], v[76:77], v[160:161]
	v_pk_fma_f32 v[78:79], v[62:63], v[78:79], v[174:175]
	v_pk_fma_f32 v[72:73], v[56:57], v[72:73], v[196:197]
	v_pk_fma_f32 v[74:75], v[58:59], v[74:75], v[210:211]
	v_cvt_pk_bf16_f32 v240, v76, v77
	v_cvt_pk_bf16_f32 v241, v78, v79
	v_cvt_pk_bf16_f32 v242, v72, v73
	v_cvt_pk_bf16_f32 v243, v74, v75
	global_store_dwordx4 v213, v[240:243], s[100:101]
	v_pk_mul_f32 v[68:69], v[68:69], v[230:231] op_sel_hi:[1,0]
	v_pk_mul_f32 v[70:71], v[70:71], v[230:231] op_sel_hi:[1,0]
	v_pk_mul_f32 v[64:65], v[64:65], v[230:231] op_sel_hi:[1,0]
	v_pk_mul_f32 v[66:67], v[66:67], v[230:231] op_sel_hi:[1,0]
	v_lshlrev_b32_e32 v160, 16, v244
	v_and_b32_e32 v161, 0xffff0000, v244
	v_lshlrev_b32_e32 v174, 16, v245
	v_and_b32_e32 v175, 0xffff0000, v245
	v_lshlrev_b32_e32 v196, 16, v246
	v_and_b32_e32 v197, 0xffff0000, v246
	v_lshlrev_b32_e32 v210, 16, v247
	v_and_b32_e32 v211, 0xffff0000, v247
	v_pk_fma_f32 v[68:69], v[52:53], v[68:69], v[160:161]
	v_pk_fma_f32 v[70:71], v[54:55], v[70:71], v[174:175]
	v_pk_fma_f32 v[64:65], v[48:49], v[64:65], v[196:197]
	v_pk_fma_f32 v[66:67], v[50:51], v[66:67], v[210:211]
	v_cvt_pk_bf16_f32 v244, v68, v69
	v_cvt_pk_bf16_f32 v245, v70, v71
	v_cvt_pk_bf16_f32 v246, v64, v65
	v_cvt_pk_bf16_f32 v247, v66, v67
	global_store_dwordx4 v213, v[244:247], s[100:101] offset:256
	s_add_u32 s100, s100, 0x8000
	s_addc_u32 s101, s101, 0
	s_waitcnt vmcnt(12)
; __device__ __forceinline__ unsigned cvt_pk_bf16(float lo, float hi) { f32x2_cv v = {lo, hi}; bf16x2_cv b = __builtin_convertvector(v, bf16x2_cv); return __builtin_bit_cast(unsigned, b); }
;     __device__ __forceinline__ void operator()(const f32x4 (&acc)[2][2][4][2], const Unit& u, int wr, int wc, int fr, int fq) const {
;     ...
;         for (int g = 0; g < 8; ++g) { const int ai = g >> 2, m = g & 3; const size_t off = (size_t)(row0 + ai * HALF + m * 16) * 1024 + col0;
;             if (g + 1 < 8) { const int ai2 = (g + 1) >> 2, m2 = (g + 1) & 3; load_x(xv[(g + 1) & 1], (size_t)(row0 + ai2 * HALF + m2 * 16) * 1024 + col0); }
;             float rs_ = 1.0f; if constexpr (ROWSCALE) rs_ = tab[((u.pm == pm0 ? 0 : 256) + ai * HALF + wr * 64 + m * 16 + fr) * 2 + 1];
; #pragma unroll
;             for (int bj = 0; bj < 2; ++bj) { const f32x4 v0 = xv[g & 1][bj][0] + gv[bj][0] * (acc[ai][bj][m][0] * rs_), v1 = xv[g & 1][bj][1] + gv[bj][1] * (acc[ai][bj][m][1] * rs_);
;                 u32x4 w; w.x = cvt_pk_bf16(v0[0], v0[1]); w.y = cvt_pk_bf16(v0[2], v0[3]); w.z = cvt_pk_bf16(v1[0], v1[1]); w.w = cvt_pk_bf16(v1[2], v1[3]);
;                 *(u32x4*)(out + off + bj * HALF) = w; } }
	v_pk_mul_f32 v[44:45], v[44:45], v[248:249] op_sel_hi:[1,0]
	v_pk_mul_f32 v[46:47], v[46:47], v[248:249] op_sel_hi:[1,0]
	v_pk_mul_f32 v[40:41], v[40:41], v[248:249] op_sel_hi:[1,0]
	v_pk_mul_f32 v[42:43], v[42:43], v[248:249] op_sel_hi:[1,0]
	v_lshlrev_b32_e32 v160, 16, v176
	v_and_b32_e32 v161, 0xffff0000, v176
	v_lshlrev_b32_e32 v174, 16, v177
	v_and_b32_e32 v175, 0xffff0000, v177
	v_lshlrev_b32_e32 v196, 16, v178
	v_and_b32_e32 v197, 0xffff0000, v178
	v_lshlrev_b32_e32 v210, 16, v179
	v_and_b32_e32 v211, 0xffff0000, v179
	v_pk_fma_f32 v[44:45], v[60:61], v[44:45], v[160:161]
	v_pk_fma_f32 v[46:47], v[62:63], v[46:47], v[174:175]
	v_pk_fma_f32 v[40:41], v[56:57], v[40:41], v[196:197]
	v_pk_fma_f32 v[42:43], v[58:59], v[42:43], v[210:211]
	v_cvt_pk_bf16_f32 v176, v44, v45
	v_cvt_pk_bf16_f32 v177, v46, v47
	v_cvt_pk_bf16_f32 v178, v40, v41
	v_cvt_pk_bf16_f32 v179, v42, v43
	global_store_dwordx4 v213, v[176:179], s[100:101]
	v_pk_mul_f32 v[36:37], v[36:37], v[248:249] op_sel_hi:[1,0]
	v_pk_mul_f32 v[38:39], v[38:39], v[248:249] op_sel_hi:[1,0]
	v_pk_mul_f32 v[32:33], v[32:33], v[248:249] op_sel_hi:[1,0]
	v_pk_mul_f32 v[34:35], v[34:35], v[248:249] op_sel_hi:[1,0]
	v_lshlrev_b32_e32 v160, 16, v180
	v_and_b32_e32 v161, 0xffff0000, v180
	v_lshlrev_b32_e32 v174, 16, v181
	v_and_b32_e32 v175, 0xffff0000, v181
	v_lshlrev_b32_e32 v196, 16, v182
	v_and_b32_e32 v197, 0xffff0000, v182
	v_lshlrev_b32_e32 v210, 16, v183
	v_and_b32_e32 v211, 0xffff0000, v183
	v_pk_fma_f32 v[36:37], v[52:53], v[36:37], v[160:161]
	v_pk_fma_f32 v[38:39], v[54:55], v[38:39], v[174:175]
	v_pk_fma_f32 v[32:33], v[48:49], v[32:33], v[196:197]
	v_pk_fma_f32 v[34:35], v[50:51], v[34:35], v[210:211]
	v_cvt_pk_bf16_f32 v180, v36, v37
	v_cvt_pk_bf16_f32 v181, v38, v39
	v_cvt_pk_bf16_f32 v182, v32, v33
	v_cvt_pk_bf16_f32 v183, v34, v35
	global_store_dwordx4 v213, v[180:183], s[100:101] offset:256
	s_add_u32 s100, s100, 0x8000
	s_addc_u32 s101, s101, 0
	s_waitcnt vmcnt(10)
	v_pk_mul_f32 v[28:29], v[28:29], v[250:251] op_sel_hi:[1,0]
	v_pk_mul_f32 v[30:31], v[30:31], v[250:251] op_sel_hi:[1,0]
	v_pk_mul_f32 v[24:25], v[24:25], v[250:251] op_sel_hi:[1,0]
	v_pk_mul_f32 v[26:27], v[26:27], v[250:251] op_sel_hi:[1,0]
	v_lshlrev_b32_e32 v160, 16, v184
	v_and_b32_e32 v161, 0xffff0000, v184
	v_lshlrev_b32_e32 v174, 16, v185
	v_and_b32_e32 v175, 0xffff0000, v185
	v_lshlrev_b32_e32 v196, 16, v186
	v_and_b32_e32 v197, 0xffff0000, v186
	v_lshlrev_b32_e32 v210, 16, v187
	v_and_b32_e32 v211, 0xffff0000, v187
	v_pk_fma_f32 v[28:29], v[60:61], v[28:29], v[160:161]
	v_pk_fma_f32 v[30:31], v[62:63], v[30:31], v[174:175]
	v_pk_fma_f32 v[24:25], v[56:57], v[24:25], v[196:197]
	v_pk_fma_f32 v[26:27], v[58:59], v[26:27], v[210:211]
	v_cvt_pk_bf16_f32 v184, v28, v29
	v_cvt_pk_bf16_f32 v185, v30, v31
	v_cvt_pk_bf16_f32 v186, v24, v25
	v_cvt_pk_bf16_f32 v187, v26, v27
	global_store_dwordx4 v213, v[184:187], s[100:101]
	v_pk_mul_f32 v[20:21], v[20:21], v[250:251] op_sel_hi:[1,0]
	v_pk_mul_f32 v[22:23], v[22:23], v[250:251] op_sel_hi:[1,0]
	v_pk_mul_f32 v[16:17], v[16:17], v[250:251] op_sel_hi:[1,0]
	v_pk_mul_f32 v[18:19], v[18:19], v[250:251] op_sel_hi:[1,0]
	v_lshlrev_b32_e32 v160, 16, v188
	v_and_b32_e32 v161, 0xffff0000, v188
	v_lshlrev_b32_e32 v174, 16, v189
	v_and_b32_e32 v175, 0xffff0000, v189
	v_lshlrev_b32_e32 v196, 16, v190
	v_and_b32_e32 v197, 0xffff0000, v190
	v_lshlrev_b32_e32 v210, 16, v191
	v_and_b32_e32 v211, 0xffff0000, v191
	v_pk_fma_f32 v[20:21], v[52:53], v[20:21], v[160:161]
	v_pk_fma_f32 v[22:23], v[54:55], v[22:23], v[174:175]
	v_pk_fma_f32 v[16:17], v[48:49], v[16:17], v[196:197]
	v_pk_fma_f32 v[18:19], v[50:51], v[18:19], v[210:211]
	v_cvt_pk_bf16_f32 v188, v20, v21
	v_cvt_pk_bf16_f32 v189, v22, v23
	v_cvt_pk_bf16_f32 v190, v16, v17
	v_cvt_pk_bf16_f32 v191, v18, v19
	global_store_dwordx4 v213, v[188:191], s[100:101] offset:256
	s_add_u32 s100, s100, 0x8000
	s_addc_u32 s101, s101, 0
	s_waitcnt vmcnt(8)
	v_pk_mul_f32 v[12:13], v[12:13], v[82:83] op_sel_hi:[1,0]
	v_pk_mul_f32 v[14:15], v[14:15], v[82:83] op_sel_hi:[1,0]
	v_pk_mul_f32 v[8:9], v[8:9], v[82:83] op_sel_hi:[1,0]
	v_pk_mul_f32 v[10:11], v[10:11], v[82:83] op_sel_hi:[1,0]
	v_lshlrev_b32_e32 v160, 16, v192
	v_and_b32_e32 v161, 0xffff0000, v192
	v_lshlrev_b32_e32 v174, 16, v193
	v_and_b32_e32 v175, 0xffff0000, v193
	v_lshlrev_b32_e32 v196, 16, v194
	v_and_b32_e32 v197, 0xffff0000, v194
	v_lshlrev_b32_e32 v210, 16, v195
	v_and_b32_e32 v211, 0xffff0000, v195
	v_pk_fma_f32 v[12:13], v[60:61], v[12:13], v[160:161]
	v_pk_fma_f32 v[14:15], v[62:63], v[14:15], v[174:175]
	v_pk_fma_f32 v[8:9], v[56:57], v[8:9], v[196:197]
	v_pk_fma_f32 v[10:11], v[58:59], v[10:11], v[210:211]
	v_cvt_pk_bf16_f32 v192, v12, v13
	v_cvt_pk_bf16_f32 v193, v14, v15
	v_cvt_pk_bf16_f32 v194, v8, v9
	v_cvt_pk_bf16_f32 v195, v10, v11
	global_store_dwordx4 v213, v[192:195], s[100:101]
	v_pk_mul_f32 v[4:5], v[4:5], v[82:83] op_sel_hi:[1,0]
	v_pk_mul_f32 v[6:7], v[6:7], v[82:83] op_sel_hi:[1,0]
	v_pk_mul_f32 v[0:1], v[0:1], v[82:83] op_sel_hi:[1,0]
	v_pk_mul_f32 v[2:3], v[2:3], v[82:83] op_sel_hi:[1,0]
	v_lshlrev_b32_e32 v160, 16, v224
	v_and_b32_e32 v161, 0xffff0000, v224
	v_lshlrev_b32_e32 v174, 16, v225
	v_and_b32_e32 v175, 0xffff0000, v225
	v_lshlrev_b32_e32 v196, 16, v226
	v_and_b32_e32 v197, 0xffff0000, v226
	v_lshlrev_b32_e32 v210, 16, v227
	v_and_b32_e32 v211, 0xffff0000, v227
	v_pk_fma_f32 v[4:5], v[52:53], v[4:5], v[160:161]
	v_pk_fma_f32 v[6:7], v[54:55], v[6:7], v[174:175]
	v_pk_fma_f32 v[0:1], v[48:49], v[0:1], v[196:197]
	v_pk_fma_f32 v[2:3], v[50:51], v[2:3], v[210:211]
	v_cvt_pk_bf16_f32 v224, v4, v5
	v_cvt_pk_bf16_f32 v225, v6, v7
	v_cvt_pk_bf16_f32 v226, v0, v1
	v_cvt_pk_bf16_f32 v227, v2, v3
	global_store_dwordx4 v213, v[224:227], s[100:101] offset:256
	s_add_u32 s100, s100, 0x8000
	s_addc_u32 s101, s101, 0
	s_mov_b64 s[4:5], -1
	s_andn2_b64 vcc, exec, s[36:37]
	s_cbranch_vccnz .LBB0_404
	s_andn2_b64 vcc, exec, s[42:43]
	s_cbranch_vccnz .LBB0_403
	s_barrier
	s_branch .LBB0_403

;     __device__ __forceinline__ void load_x(f32x4 (&x)[2][2], size_t off) const {
; #pragma unroll
;         for (int bj = 0; bj < 2; ++bj) {
;             if constexpr (XIN_F32) { x[bj][0] = *(const f32x4*)((const float*)xin + off + bj * HALF); x[bj][1] = *(const f32x4*)((const float*)xin + off + bj * HALF + 4); }
;             else { const u32x4 w = *(const u32x4*)((const bf16_t*)xin + off + bj * HALF);
;                 x[bj][0] = (f32x4){__builtin_bit_cast(float, w.x << 16), __builtin_bit_cast(float, w.x & 0xffff0000u), __builtin_bit_cast(float, w.y << 16), __builtin_bit_cast(float, w.y & 0xffff0000u)};
;                 x[bj][1] = (f32x4){__builtin_bit_cast(float, w.z << 16), __builtin_bit_cast(float, w.z & 0xffff0000u), __builtin_bit_cast(float, w.w << 16), __builtin_bit_cast(float, w.w & 0xffff0000u)}; } }
;     }
;     __device__ __forceinline__ void operator()(const f32x4 (&acc)[2][2][4][2], const Unit& u, int wr, int wc, int fr, int fq) const {
;         const int row0 = u.pm * BM + wr * 64 + fr; const int col0 = u.pn * BM + wc * 32 + 8 * fq;
;         const int b = (u.pm * BM) >> 12;
;         f32x4 gv[2][2];
; #pragma unroll
;         for (int bj = 0; bj < 2; ++bj)
; #pragma unroll
;             for (int n = 0; n < 2; ++n) gv[bj][n] = *(const f32x4*)(gate + (size_t)b * gate_ld + col0 + bj * HALF + n * 4);
;         f32x4 xv[2][2][2];
;         load_x(xv[0], (size_t)row0 * 1024 + col0);
; #pragma unroll
;         for (int g = 0; g < 8; ++g) { const int ai = g >> 2, m = g & 3; const size_t off = (size_t)(row0 + ai * HALF + m * 16) * 1024 + col0;
;             if (g + 1 < 8) { const int ai2 = (g + 1) >> 2, m2 = (g + 1) & 3; load_x(xv[(g + 1) & 1], (size_t)(row0 + ai2 * HALF + m2 * 16) * 1024 + col0); }
;             float rs_ = 1.0f; if constexpr (ROWSCALE) rs_ = tab[((u.pm == pm0 ? 0 : 256) + ai * HALF + wr * 64 + m * 16 + fr) * 2 + 1];
; #pragma unroll
;             for (int bj = 0; bj < 2; ++bj) { const f32x4 v0 = xv[g & 1][bj][0] + gv[bj][0] * (acc[ai][bj][m][0] * rs_), v1 = xv[g & 1][bj][1] + gv[bj][1] * (acc[ai][bj][m][1] * rs_);
;                 u32x4 w; w.x = cvt_pk_bf16(v0[0], v0[1]); w.y = cvt_pk_bf16(v0[2], v0[3]); w.z = cvt_pk_bf16(v1[0], v1[1]); w.w = cvt_pk_bf16(v1[2], v1[3]);
;                 *(u32x4*)(out + off + bj * HALF) = w; } }
.LBB0_445:
	s_ashr_i32 s3, s4, 4
	v_lshl_or_b32 v205, s5, 8, v191
	s_mul_hi_i32 s5, s3, 0x6000
	s_mulk_i32 s3, 0x6000
	v_readlane_b32 s80, v254, 4
	s_add_u32 s12, s64, s3
	v_readlane_b32 s81, v254, 5
	s_addc_u32 s13, s65, s5
	v_lshlrev_b32_e32 v211, 2, v205
	global_load_dwordx4 v[76:79], v211, s[12:13]
	global_load_dwordx4 v[72:75], v211, s[12:13] offset:16
	global_load_dwordx4 v[68:71], v211, s[12:13] offset:512
	global_load_dwordx4 v[64:67], v211, s[12:13] offset:528
	v_lshl_add_u32 v185, v186, 12, v211
	v_lshlrev_b32_e32 v195, 11, v186
	v_lshl_add_u32 v195, v205, 1, v195
	s_lshl_b32 s3, s4, 20
	s_add_u32 s98, s80, s3
	s_addc_u32 s99, s81, 0
	s_lshl_b32 s3, s4, 19
	s_add_u32 s100, s38, s3
	s_addc_u32 s101, s39, 0
	global_load_dwordx4 v[148:151], v185, s[98:99] nt
	global_load_dwordx4 v[152:155], v185, s[98:99] offset:16 nt
	global_load_dwordx4 v[180:183], v185, s[98:99] offset:512 nt
	global_load_dwordx4 v[196:199], v185, s[98:99] offset:528 nt
	s_add_u32 s98, s98, 0x10000
	s_addc_u32 s99, s99, 0
	global_load_dwordx4 v[200:203], v185, s[98:99] nt
	global_load_dwordx4 v[220:223], v185, s[98:99] offset:16 nt
	global_load_dwordx4 v[224:227], v185, s[98:99] offset:512 nt
	global_load_dwordx4 v[228:231], v185, s[98:99] offset:528 nt
	s_add_u32 s98, s98, 0x10000
	s_addc_u32 s99, s99, 0
	global_load_dwordx4 v[236:239], v185, s[98:99] nt
	global_load_dwordx4 v[240:243], v185, s[98:99] offset:16 nt
	global_load_dwordx4 v[244:247], v185, s[98:99] offset:512 nt
	global_load_dwordx4 v[248:251], v185, s[98:99] offset:528 nt
	s_add_u32 s98, s98, 0x10000
	s_addc_u32 s99, s99, 0
	v_readlane_b32 s3, v255, 49
	s_nop 0
	s_cmp_eq_u32 s4, s3
	s_cselect_b32 s4, 0, 0x100
	v_add_u32_e32 v83, s4, v186
	s_add_i32 s5, 0, 0x22800
	v_lshl_add_u32 v83, v83, 3, s5
	s_andn2_b64 vcc, exec, s[36:37]
	s_mov_b32 s78, s1
	v_readlane_b32 s82, v254, 6
	v_readlane_b32 s83, v254, 7
	v_readlane_b32 s84, v254, 8
	v_readlane_b32 s85, v254, 9
	v_readlane_b32 s86, v254, 10
	v_readlane_b32 s87, v254, 11
	v_readlane_b32 s88, v254, 12
	v_readlane_b32 s89, v254, 13
	v_readlane_b32 s90, v254, 14
	v_readlane_b32 s91, v254, 15
	v_readlane_b32 s92, v254, 16
	v_readlane_b32 s93, v254, 17
	v_readlane_b32 s94, v254, 18
	v_readlane_b32 s95, v254, 19
	ds_read_b32 v184, v83 offset:4
	ds_read_b32 v194, v83 offset:132
	ds_read_b32 v204, v83 offset:260
	ds_read_b32 v210, v83 offset:388
	ds_read_b32 v232, v83 offset:1028
	ds_read_b32 v234, v83 offset:1156
	ds_read_b32 v82, v83 offset:1284
	ds_read_b32 v80, v83 offset:1412
	s_waitcnt lgkmcnt(0)
	s_waitcnt vmcnt(8)
	v_pk_mul_f32 v[144:145], v[144:145], v[184:185] op_sel_hi:[1,0]
	v_pk_mul_f32 v[146:147], v[146:147], v[184:185] op_sel_hi:[1,0]
	v_pk_mul_f32 v[140:141], v[140:141], v[184:185] op_sel_hi:[1,0]
	v_pk_mul_f32 v[142:143], v[142:143], v[184:185] op_sel_hi:[1,0]
	v_pk_fma_f32 v[144:145], v[76:77], v[144:145], v[148:149]
	v_pk_fma_f32 v[146:147], v[78:79], v[146:147], v[150:151]
	v_pk_fma_f32 v[140:141], v[72:73], v[140:141], v[152:153]
	v_pk_fma_f32 v[142:143], v[74:75], v[142:143], v[154:155]
	v_cvt_pk_bf16_f32 v148, v144, v145
	v_cvt_pk_bf16_f32 v149, v146, v147
	v_cvt_pk_bf16_f32 v150, v140, v141
	v_cvt_pk_bf16_f32 v151, v142, v143
	global_store_dwordx4 v195, v[148:151], s[100:101]
	v_pk_mul_f32 v[136:137], v[136:137], v[184:185] op_sel_hi:[1,0]
	v_pk_mul_f32 v[138:139], v[138:139], v[184:185] op_sel_hi:[1,0]
	v_pk_mul_f32 v[132:133], v[132:133], v[184:185] op_sel_hi:[1,0]
	v_pk_mul_f32 v[134:135], v[134:135], v[184:185] op_sel_hi:[1,0]
	v_pk_fma_f32 v[136:137], v[68:69], v[136:137], v[180:181]
	v_pk_fma_f32 v[138:139], v[70:71], v[138:139], v[182:183]
	v_pk_fma_f32 v[132:133], v[64:65], v[132:133], v[196:197]
	v_pk_fma_f32 v[134:135], v[66:67], v[134:135], v[198:199]
	v_cvt_pk_bf16_f32 v180, v136, v137
	v_cvt_pk_bf16_f32 v181, v138, v139
	v_cvt_pk_bf16_f32 v182, v132, v133
	v_cvt_pk_bf16_f32 v183, v134, v135
	global_store_dwordx4 v195, v[180:183], s[100:101] offset:256
	s_add_u32 s100, s100, 0x8000
	s_addc_u32 s101, s101, 0
	global_load_dwordx4 v[148:151], v185, s[98:99] nt
	global_load_dwordx4 v[152:155], v185, s[98:99] offset:16 nt
	global_load_dwordx4 v[180:183], v185, s[98:99] offset:512 nt
	global_load_dwordx4 v[196:199], v185, s[98:99] offset:528 nt
	s_add_u32 s98, s98, 0x50000
	s_addc_u32 s99, s99, 0
	s_waitcnt vmcnt(10)
	v_pk_mul_f32 v[128:129], v[128:129], v[194:195] op_sel_hi:[1,0]
	v_pk_mul_f32 v[130:131], v[130:131], v[194:195] op_sel_hi:[1,0]
	v_pk_mul_f32 v[124:125], v[124:125], v[194:195] op_sel_hi:[1,0]
	v_pk_mul_f32 v[126:127], v[126:127], v[194:195] op_sel_hi:[1,0]
	v_pk_fma_f32 v[128:129], v[76:77], v[128:129], v[200:201]
	v_pk_fma_f32 v[130:131], v[78:79], v[130:131], v[202:203]
	v_pk_fma_f32 v[124:125], v[72:73], v[124:125], v[220:221]
	v_pk_fma_f32 v[126:127], v[74:75], v[126:127], v[222:223]
	v_cvt_pk_bf16_f32 v200, v128, v129
	v_cvt_pk_bf16_f32 v201, v130, v131
	v_cvt_pk_bf16_f32 v202, v124, v125
	v_cvt_pk_bf16_f32 v203, v126, v127
	global_store_dwordx4 v195, v[200:203], s[100:101]
	v_pk_mul_f32 v[120:121], v[120:121], v[194:195] op_sel_hi:[1,0]
	v_pk_mul_f32 v[122:123], v[122:123], v[194:195] op_sel_hi:[1,0]
	v_pk_mul_f32 v[116:117], v[116:117], v[194:195] op_sel_hi:[1,0]
	v_pk_mul_f32 v[118:119], v[118:119], v[194:195] op_sel_hi:[1,0]
	v_pk_fma_f32 v[120:121], v[68:69], v[120:121], v[224:225]
	v_pk_fma_f32 v[122:123], v[70:71], v[122:123], v[226:227]
	v_pk_fma_f32 v[116:117], v[64:65], v[116:117], v[228:229]
	v_pk_fma_f32 v[118:119], v[66:67], v[118:119], v[230:231]
	v_cvt_pk_bf16_f32 v224, v120, v121
	v_cvt_pk_bf16_f32 v225, v122, v123
	v_cvt_pk_bf16_f32 v226, v116, v117
	v_cvt_pk_bf16_f32 v227, v118, v119
	global_store_dwordx4 v195, v[224:227], s[100:101] offset:256
	s_add_u32 s100, s100, 0x8000
	s_addc_u32 s101, s101, 0
	global_load_dwordx4 v[200:203], v185, s[98:99] nt
	global_load_dwordx4 v[220:223], v185, s[98:99] offset:16 nt
	global_load_dwordx4 v[224:227], v185, s[98:99] offset:512 nt
	global_load_dwordx4 v[228:231], v185, s[98:99] offset:528 nt
	s_add_u32 s98, s98, 0x10000
	s_addc_u32 s99, s99, 0
	s_waitcnt vmcnt(12)
; __device__ __forceinline__ unsigned cvt_pk_bf16(float lo, float hi) { f32x2_cv v = {lo, hi}; bf16x2_cv b = __builtin_convertvector(v, bf16x2_cv); return __builtin_bit_cast(unsigned, b); }
;     __device__ __forceinline__ void operator()(const f32x4 (&acc)[2][2][4][2], const Unit& u, int wr, int wc, int fr, int fq) const {
;     ...
;         for (int g = 0; g < 8; ++g) { const int ai = g >> 2, m = g & 3; const size_t off = (size_t)(row0 + ai * HALF + m * 16) * 1024 + col0;
;             if (g + 1 < 8) { const int ai2 = (g + 1) >> 2, m2 = (g + 1) & 3; load_x(xv[(g + 1) & 1], (size_t)(row0 + ai2 * HALF + m2 * 16) * 1024 + col0); }
;             float rs_ = 1.0f; if constexpr (ROWSCALE) rs_ = tab[((u.pm == pm0 ? 0 : 256) + ai * HALF + wr * 64 + m * 16 + fr) * 2 + 1];
; #pragma unroll
;             for (int bj = 0; bj < 2; ++bj) { const f32x4 v0 = xv[g & 1][bj][0] + gv[bj][0] * (acc[ai][bj][m][0] * rs_), v1 = xv[g & 1][bj][1] + gv[bj][1] * (acc[ai][bj][m][1] * rs_);
;                 u32x4 w; w.x = cvt_pk_bf16(v0[0], v0[1]); w.y = cvt_pk_bf16(v0[2], v0[3]); w.z = cvt_pk_bf16(v1[0], v1[1]); w.w = cvt_pk_bf16(v1[2], v1[3]);
;                 *(u32x4*)(out + off + bj * HALF) = w; } }
	v_pk_mul_f32 v[112:113], v[112:113], v[204:205] op_sel_hi:[1,0]
	v_pk_mul_f32 v[114:115], v[114:115], v[204:205] op_sel_hi:[1,0]
	v_pk_mul_f32 v[108:109], v[108:109], v[204:205] op_sel_hi:[1,0]
	v_pk_mul_f32 v[110:111], v[110:111], v[204:205] op_sel_hi:[1,0]
	v_pk_fma_f32 v[112:113], v[76:77], v[112:113], v[236:237]
	v_pk_fma_f32 v[114:115], v[78:79], v[114:115], v[238:239]
	v_pk_fma_f32 v[108:109], v[72:73], v[108:109], v[240:241]
	v_pk_fma_f32 v[110:111], v[74:75], v[110:111], v[242:243]
	v_cvt_pk_bf16_f32 v236, v112, v113
	v_cvt_pk_bf16_f32 v237, v114, v115
	v_cvt_pk_bf16_f32 v238, v108, v109
	v_cvt_pk_bf16_f32 v239, v110, v111
	global_store_dwordx4 v195, v[236:239], s[100:101]
	v_pk_mul_f32 v[104:105], v[104:105], v[204:205] op_sel_hi:[1,0]
	v_pk_mul_f32 v[106:107], v[106:107], v[204:205] op_sel_hi:[1,0]
	v_pk_mul_f32 v[100:101], v[100:101], v[204:205] op_sel_hi:[1,0]
	v_pk_mul_f32 v[102:103], v[102:103], v[204:205] op_sel_hi:[1,0]
	v_pk_fma_f32 v[104:105], v[68:69], v[104:105], v[244:245]
	v_pk_fma_f32 v[106:107], v[70:71], v[106:107], v[246:247]
	v_pk_fma_f32 v[100:101], v[64:65], v[100:101], v[248:249]
	v_pk_fma_f32 v[102:103], v[66:67], v[102:103], v[250:251]
	v_cvt_pk_bf16_f32 v244, v104, v105
	v_cvt_pk_bf16_f32 v245, v106, v107
	v_cvt_pk_bf16_f32 v246, v100, v101
	v_cvt_pk_bf16_f32 v247, v102, v103
	global_store_dwordx4 v195, v[244:247], s[100:101] offset:256
	s_add_u32 s100, s100, 0x8000
	s_addc_u32 s101, s101, 0
	global_load_dwordx4 v[236:239], v185, s[98:99] nt
	global_load_dwordx4 v[240:243], v185, s[98:99] offset:16 nt
	global_load_dwordx4 v[244:247], v185, s[98:99] offset:512 nt
	global_load_dwordx4 v[248:251], v185, s[98:99] offset:528 nt
	s_add_u32 s98, s98, 0x10000
	s_addc_u32 s99, s99, 0
	s_waitcnt vmcnt(12)
	v_pk_mul_f32 v[96:97], v[96:97], v[210:211] op_sel_hi:[1,0]
	v_pk_mul_f32 v[98:99], v[98:99], v[210:211] op_sel_hi:[1,0]
	v_pk_mul_f32 v[92:93], v[92:93], v[210:211] op_sel_hi:[1,0]
	v_pk_mul_f32 v[94:95], v[94:95], v[210:211] op_sel_hi:[1,0]
	v_pk_fma_f32 v[96:97], v[76:77], v[96:97], v[148:149]
	v_pk_fma_f32 v[98:99], v[78:79], v[98:99], v[150:151]
	v_pk_fma_f32 v[92:93], v[72:73], v[92:93], v[152:153]
	v_pk_fma_f32 v[94:95], v[74:75], v[94:95], v[154:155]
	v_cvt_pk_bf16_f32 v148, v96, v97
	v_cvt_pk_bf16_f32 v149, v98, v99
	v_cvt_pk_bf16_f32 v150, v92, v93
	v_cvt_pk_bf16_f32 v151, v94, v95
	global_store_dwordx4 v195, v[148:151], s[100:101]
	v_pk_mul_f32 v[88:89], v[88:89], v[210:211] op_sel_hi:[1,0]
	v_pk_mul_f32 v[90:91], v[90:91], v[210:211] op_sel_hi:[1,0]
	v_pk_mul_f32 v[84:85], v[84:85], v[210:211] op_sel_hi:[1,0]
	v_pk_mul_f32 v[86:87], v[86:87], v[210:211] op_sel_hi:[1,0]
	v_pk_fma_f32 v[88:89], v[68:69], v[88:89], v[180:181]
	v_pk_fma_f32 v[90:91], v[70:71], v[90:91], v[182:183]
	v_pk_fma_f32 v[84:85], v[64:65], v[84:85], v[196:197]
	v_pk_fma_f32 v[86:87], v[66:67], v[86:87], v[198:199]
	v_cvt_pk_bf16_f32 v180, v88, v89
	v_cvt_pk_bf16_f32 v181, v90, v91
	v_cvt_pk_bf16_f32 v182, v84, v85
	v_cvt_pk_bf16_f32 v183, v86, v87
	global_store_dwordx4 v195, v[180:183], s[100:101] offset:256
	s_add_u32 s100, s100, 0x28000
	s_addc_u32 s101, s101, 0
	global_load_dwordx4 v[148:151], v185, s[98:99] nt
	global_load_dwordx4 v[152:155], v185, s[98:99] offset:16 nt
	global_load_dwordx4 v[180:183], v185, s[98:99] offset:512 nt
	global_load_dwordx4 v[196:199], v185, s[98:99] offset:528 nt
	s_add_u32 s98, s98, 0x10000
	s_addc_u32 s99, s99, 0
	s_waitcnt vmcnt(12)
	v_pk_mul_f32 v[60:61], v[60:61], v[232:233] op_sel_hi:[1,0]
	v_pk_mul_f32 v[62:63], v[62:63], v[232:233] op_sel_hi:[1,0]
	v_pk_mul_f32 v[56:57], v[56:57], v[232:233] op_sel_hi:[1,0]
	v_pk_mul_f32 v[58:59], v[58:59], v[232:233] op_sel_hi:[1,0]
	v_pk_fma_f32 v[60:61], v[76:77], v[60:61], v[200:201]
	v_pk_fma_f32 v[62:63], v[78:79], v[62:63], v[202:203]
	v_pk_fma_f32 v[56:57], v[72:73], v[56:57], v[220:221]
	v_pk_fma_f32 v[58:59], v[74:75], v[58:59], v[222:223]
	v_cvt_pk_bf16_f32 v200, v60, v61
	v_cvt_pk_bf16_f32 v201, v62, v63
	v_cvt_pk_bf16_f32 v202, v56, v57
	v_cvt_pk_bf16_f32 v203, v58, v59
	global_store_dwordx4 v195, v[200:203], s[100:101]
	v_pk_mul_f32 v[52:53], v[52:53], v[232:233] op_sel_hi:[1,0]
	v_pk_mul_f32 v[54:55], v[54:55], v[232:233] op_sel_hi:[1,0]
	v_pk_mul_f32 v[48:49], v[48:49], v[232:233] op_sel_hi:[1,0]
	v_pk_mul_f32 v[50:51], v[50:51], v[232:233] op_sel_hi:[1,0]
	v_pk_fma_f32 v[52:53], v[68:69], v[52:53], v[224:225]
	v_pk_fma_f32 v[54:55], v[70:71], v[54:55], v[226:227]
	v_pk_fma_f32 v[48:49], v[64:65], v[48:49], v[228:229]
	v_pk_fma_f32 v[50:51], v[66:67], v[50:51], v[230:231]
	v_cvt_pk_bf16_f32 v224, v52, v53
	v_cvt_pk_bf16_f32 v225, v54, v55
	v_cvt_pk_bf16_f32 v226, v48, v49
	v_cvt_pk_bf16_f32 v227, v50, v51
	global_store_dwordx4 v195, v[224:227], s[100:101] offset:256
	s_add_u32 s100, s100, 0x8000
	s_addc_u32 s101, s101, 0
	global_load_dwordx4 v[200:203], v185, s[98:99] nt
	global_load_dwordx4 v[220:223], v185, s[98:99] offset:16 nt
	global_load_dwordx4 v[224:227], v185, s[98:99] offset:512 nt
	global_load_dwordx4 v[228:231], v185, s[98:99] offset:528 nt
	s_add_u32 s98, s98, 0x10000
	s_addc_u32 s99, s99, 0
	s_waitcnt vmcnt(12)
; __device__ __forceinline__ unsigned cvt_pk_bf16(float lo, float hi) { f32x2_cv v = {lo, hi}; bf16x2_cv b = __builtin_convertvector(v, bf16x2_cv); return __builtin_bit_cast(unsigned, b); }
;     __device__ __forceinline__ void operator()(const f32x4 (&acc)[2][2][4][2], const Unit& u, int wr, int wc, int fr, int fq) const {
;     ...
;         for (int g = 0; g < 8; ++g) { const int ai = g >> 2, m = g & 3; const size_t off = (size_t)(row0 + ai * HALF + m * 16) * 1024 + col0;
;             if (g + 1 < 8) { const int ai2 = (g + 1) >> 2, m2 = (g + 1) & 3; load_x(xv[(g + 1) & 1], (size_t)(row0 + ai2 * HALF + m2 * 16) * 1024 + col0); }
;             float rs_ = 1.0f; if constexpr (ROWSCALE) rs_ = tab[((u.pm == pm0 ? 0 : 256) + ai * HALF + wr * 64 + m * 16 + fr) * 2 + 1];
; #pragma unroll
;             for (int bj = 0; bj < 2; ++bj) { const f32x4 v0 = xv[g & 1][bj][0] + gv[bj][0] * (acc[ai][bj][m][0] * rs_), v1 = xv[g & 1][bj][1] + gv[bj][1] * (acc[ai][bj][m][1] * rs_);
;                 u32x4 w; w.x = cvt_pk_bf16(v0[0], v0[1]); w.y = cvt_pk_bf16(v0[2], v0[3]); w.z = cvt_pk_bf16(v1[0], v1[1]); w.w = cvt_pk_bf16(v1[2], v1[3]);
;                 *(u32x4*)(out + off + bj * HALF) = w; } }
	v_pk_mul_f32 v[44:45], v[44:45], v[234:235] op_sel_hi:[1,0]
	v_pk_mul_f32 v[46:47], v[46:47], v[234:235] op_sel_hi:[1,0]
	v_pk_mul_f32 v[40:41], v[40:41], v[234:235] op_sel_hi:[1,0]
	v_pk_mul_f32 v[42:43], v[42:43], v[234:235] op_sel_hi:[1,0]
	v_pk_fma_f32 v[44:45], v[76:77], v[44:45], v[236:237]
	v_pk_fma_f32 v[46:47], v[78:79], v[46:47], v[238:239]
	v_pk_fma_f32 v[40:41], v[72:73], v[40:41], v[240:241]
	v_pk_fma_f32 v[42:43], v[74:75], v[42:43], v[242:243]
	v_cvt_pk_bf16_f32 v236, v44, v45
	v_cvt_pk_bf16_f32 v237, v46, v47
	v_cvt_pk_bf16_f32 v238, v40, v41
	v_cvt_pk_bf16_f32 v239, v42, v43
	global_store_dwordx4 v195, v[236:239], s[100:101]
	v_pk_mul_f32 v[36:37], v[36:37], v[234:235] op_sel_hi:[1,0]
	v_pk_mul_f32 v[38:39], v[38:39], v[234:235] op_sel_hi:[1,0]
	v_pk_mul_f32 v[32:33], v[32:33], v[234:235] op_sel_hi:[1,0]
	v_pk_mul_f32 v[34:35], v[34:35], v[234:235] op_sel_hi:[1,0]
	v_pk_fma_f32 v[36:37], v[68:69], v[36:37], v[244:245]
	v_pk_fma_f32 v[38:39], v[70:71], v[38:39], v[246:247]
	v_pk_fma_f32 v[32:33], v[64:65], v[32:33], v[248:249]
	v_pk_fma_f32 v[34:35], v[66:67], v[34:35], v[250:251]
	v_cvt_pk_bf16_f32 v244, v36, v37
	v_cvt_pk_bf16_f32 v245, v38, v39
	v_cvt_pk_bf16_f32 v246, v32, v33
	v_cvt_pk_bf16_f32 v247, v34, v35
	global_store_dwordx4 v195, v[244:247], s[100:101] offset:256
	s_add_u32 s100, s100, 0x8000
	s_addc_u32 s101, s101, 0
	s_waitcnt vmcnt(8)
	v_pk_mul_f32 v[28:29], v[28:29], v[82:83] op_sel_hi:[1,0]
	v_pk_mul_f32 v[30:31], v[30:31], v[82:83] op_sel_hi:[1,0]
	v_pk_mul_f32 v[24:25], v[24:25], v[82:83] op_sel_hi:[1,0]
	v_pk_mul_f32 v[26:27], v[26:27], v[82:83] op_sel_hi:[1,0]
	v_pk_fma_f32 v[28:29], v[76:77], v[28:29], v[148:149]
	v_pk_fma_f32 v[30:31], v[78:79], v[30:31], v[150:151]
	v_pk_fma_f32 v[24:25], v[72:73], v[24:25], v[152:153]
	v_pk_fma_f32 v[26:27], v[74:75], v[26:27], v[154:155]
	v_cvt_pk_bf16_f32 v148, v28, v29
	v_cvt_pk_bf16_f32 v149, v30, v31
	v_cvt_pk_bf16_f32 v150, v24, v25
	v_cvt_pk_bf16_f32 v151, v26, v27
	global_store_dwordx4 v195, v[148:151], s[100:101]
	v_pk_mul_f32 v[20:21], v[20:21], v[82:83] op_sel_hi:[1,0]
	v_pk_mul_f32 v[22:23], v[22:23], v[82:83] op_sel_hi:[1,0]
	v_pk_mul_f32 v[16:17], v[16:17], v[82:83] op_sel_hi:[1,0]
	v_pk_mul_f32 v[18:19], v[18:19], v[82:83] op_sel_hi:[1,0]
	v_pk_fma_f32 v[20:21], v[68:69], v[20:21], v[180:181]
	v_pk_fma_f32 v[22:23], v[70:71], v[22:23], v[182:183]
	v_pk_fma_f32 v[16:17], v[64:65], v[16:17], v[196:197]
	v_pk_fma_f32 v[18:19], v[66:67], v[18:19], v[198:199]
	v_cvt_pk_bf16_f32 v180, v20, v21
	v_cvt_pk_bf16_f32 v181, v22, v23
	v_cvt_pk_bf16_f32 v182, v16, v17
	v_cvt_pk_bf16_f32 v183, v18, v19
	global_store_dwordx4 v195, v[180:183], s[100:101] offset:256
	s_add_u32 s100, s100, 0x8000
	s_addc_u32 s101, s101, 0
	s_waitcnt vmcnt(4)
	v_pk_mul_f32 v[12:13], v[12:13], v[80:81] op_sel_hi:[1,0]
	v_pk_mul_f32 v[14:15], v[14:15], v[80:81] op_sel_hi:[1,0]
	v_pk_mul_f32 v[8:9], v[8:9], v[80:81] op_sel_hi:[1,0]
	v_pk_mul_f32 v[10:11], v[10:11], v[80:81] op_sel_hi:[1,0]
	v_pk_fma_f32 v[12:13], v[76:77], v[12:13], v[200:201]
	v_pk_fma_f32 v[14:15], v[78:79], v[14:15], v[202:203]
	v_pk_fma_f32 v[8:9], v[72:73], v[8:9], v[220:221]
	v_pk_fma_f32 v[10:11], v[74:75], v[10:11], v[222:223]
	v_cvt_pk_bf16_f32 v200, v12, v13
	v_cvt_pk_bf16_f32 v201, v14, v15
	v_cvt_pk_bf16_f32 v202, v8, v9
	v_cvt_pk_bf16_f32 v203, v10, v11
	global_store_dwordx4 v195, v[200:203], s[100:101]
	v_pk_mul_f32 v[4:5], v[4:5], v[80:81] op_sel_hi:[1,0]
	v_pk_mul_f32 v[6:7], v[6:7], v[80:81] op_sel_hi:[1,0]
	v_pk_mul_f32 v[0:1], v[0:1], v[80:81] op_sel_hi:[1,0]
	v_pk_mul_f32 v[2:3], v[2:3], v[80:81] op_sel_hi:[1,0]
	v_pk_fma_f32 v[4:5], v[68:69], v[4:5], v[224:225]
	v_pk_fma_f32 v[6:7], v[70:71], v[6:7], v[226:227]
	v_pk_fma_f32 v[0:1], v[64:65], v[0:1], v[228:229]
	v_pk_fma_f32 v[2:3], v[66:67], v[2:3], v[230:231]
	v_cvt_pk_bf16_f32 v224, v4, v5
	v_cvt_pk_bf16_f32 v225, v6, v7
	v_cvt_pk_bf16_f32 v226, v0, v1
	v_cvt_pk_bf16_f32 v227, v2, v3
	global_store_dwordx4 v195, v[224:227], s[100:101] offset:256
	s_add_u32 s100, s100, 0x8000
	s_addc_u32 s101, s101, 0
	s_mov_b64 s[4:5], -1
	s_cbranch_vccnz .LBB0_432
	s_andn2_b64 vcc, exec, s[40:41]
	s_cbranch_vccnz .LBB0_431
	s_barrier
	s_branch .LBB0_431

;     __device__ __forceinline__ void load_x(f32x4 (&x)[2][2], size_t off) const {
; #pragma unroll
;         for (int bj = 0; bj < 2; ++bj) {
;             if constexpr (XIN_F32) { x[bj][0] = *(const f32x4*)((const float*)xin + off + bj * HALF); x[bj][1] = *(const f32x4*)((const float*)xin + off + bj * HALF + 4); }
;             else { const u32x4 w = *(const u32x4*)((const bf16_t*)xin + off + bj * HALF);
;                 x[bj][0] = (f32x4){__builtin_bit_cast(float, w.x << 16), __builtin_bit_cast(float, w.x & 0xffff0000u), __builtin_bit_cast(float, w.y << 16), __builtin_bit_cast(float, w.y & 0xffff0000u)};
;                 x[bj][1] = (f32x4){__builtin_bit_cast(float, w.z << 16), __builtin_bit_cast(float, w.z & 0xffff0000u), __builtin_bit_cast(float, w.w << 16), __builtin_bit_cast(float, w.w & 0xffff0000u)}; } }
;     }
;     __device__ __forceinline__ void operator()(const f32x4 (&acc)[2][2][4][2], const Unit& u, int wr, int wc, int fr, int fq) const {
;         const int row0 = u.pm * BM + wr * 64 + fr; const int col0 = u.pn * BM + wc * 32 + 8 * fq;
;         const int b = (u.pm * BM) >> 12;
;         f32x4 gv[2][2];
; #pragma unroll
;         for (int bj = 0; bj < 2; ++bj)
; #pragma unroll
;             for (int n = 0; n < 2; ++n) gv[bj][n] = *(const f32x4*)(gate + (size_t)b * gate_ld + col0 + bj * HALF + n * 4);
;         f32x4 xv[2][2][2];
;         load_x(xv[0], (size_t)row0 * 1024 + col0);
; #pragma unroll
;         for (int g = 0; g < 8; ++g) { const int ai = g >> 2, m = g & 3; const size_t off = (size_t)(row0 + ai * HALF + m * 16) * 1024 + col0;
;             if (g + 1 < 8) { const int ai2 = (g + 1) >> 2, m2 = (g + 1) & 3; load_x(xv[(g + 1) & 1], (size_t)(row0 + ai2 * HALF + m2 * 16) * 1024 + col0); }
;             float rs_ = 1.0f; if constexpr (ROWSCALE) rs_ = tab[((u.pm == pm0 ? 0 : 256) + ai * HALF + wr * 64 + m * 16 + fr) * 2 + 1];
; #pragma unroll
;             for (int bj = 0; bj < 2; ++bj) { const f32x4 v0 = xv[g & 1][bj][0] + gv[bj][0] * (acc[ai][bj][m][0] * rs_), v1 = xv[g & 1][bj][1] + gv[bj][1] * (acc[ai][bj][m][1] * rs_);
;                 u32x4 w; w.x = cvt_pk_bf16(v0[0], v0[1]); w.y = cvt_pk_bf16(v0[2], v0[3]); w.z = cvt_pk_bf16(v1[0], v1[1]); w.w = cvt_pk_bf16(v1[2], v1[3]);
;                 *(u32x4*)(out + off + bj * HALF) = w; } }
.LBB0_708:
	s_ashr_i32 s3, s65, 4
	s_mul_hi_i32 s5, s3, 0x6000
	s_mulk_i32 s3, 0x6000
	s_add_u32 s4, s57, s3
	s_addc_u32 s5, s58, s5
	v_lshl_or_b32 v213, s66, 8, v194
	v_lshlrev_b32_e32 v220, 2, v213
	global_load_dwordx4 v[60:63], v220, s[4:5]
	global_load_dwordx4 v[56:59], v220, s[4:5] offset:16
	global_load_dwordx4 v[52:55], v220, s[4:5] offset:512
	global_load_dwordx4 v[48:51], v220, s[4:5] offset:528
	v_lshlrev_b32_e32 v212, 11, v192
	v_lshl_add_u32 v212, v213, 1, v212
	s_lshl_b32 s3, s65, 19
	s_add_u32 s98, s40, s3
	s_addc_u32 s99, s41, 0
	s_mov_b64 s[100:101], s[98:99]
	global_load_dwordx4 v[156:159], v212, s[98:99] nt
	global_load_dwordx4 v[176:179], v212, s[98:99] offset:256 nt
	s_add_u32 s98, s98, 0x8000
	s_addc_u32 s99, s99, 0
	global_load_dwordx4 v[180:183], v212, s[98:99] nt
	global_load_dwordx4 v[184:187], v212, s[98:99] offset:256 nt
	s_add_u32 s98, s98, 0x8000
	s_addc_u32 s99, s99, 0
	global_load_dwordx4 v[188:191], v212, s[98:99] nt
	global_load_dwordx4 v[196:199], v212, s[98:99] offset:256 nt
	s_add_u32 s98, s98, 0x8000
	s_addc_u32 s99, s99, 0
	global_load_dwordx4 v[200:203], v212, s[98:99] nt
	global_load_dwordx4 v[224:227], v212, s[98:99] offset:256 nt
	s_add_u32 s98, s98, 0x28000
	s_addc_u32 s99, s99, 0
	global_load_dwordx4 v[228:231], v212, s[98:99] nt
	global_load_dwordx4 v[232:235], v212, s[98:99] offset:256 nt
	s_add_u32 s98, s98, 0x8000
	s_addc_u32 s99, s99, 0
	s_waitcnt vmcnt(8)
	v_lshlrev_b32_e32 v160, 16, v156
	v_and_b32_e32 v161, 0xffff0000, v156
	v_lshlrev_b32_e32 v174, 16, v157
	v_and_b32_e32 v175, 0xffff0000, v157
	v_lshlrev_b32_e32 v204, 16, v158
	v_and_b32_e32 v205, 0xffff0000, v158
	v_lshlrev_b32_e32 v210, 16, v159
	v_and_b32_e32 v211, 0xffff0000, v159
	v_pk_fma_f32 v[142:143], v[142:143], v[60:61], v[160:161]
	v_pk_fma_f32 v[144:145], v[144:145], v[62:63], v[174:175]
	v_pk_fma_f32 v[138:139], v[138:139], v[56:57], v[204:205]
	v_pk_fma_f32 v[140:141], v[140:141], v[58:59], v[210:211]
	v_cvt_pk_bf16_f32 v156, v142, v143
	v_cvt_pk_bf16_f32 v157, v144, v145
	v_cvt_pk_bf16_f32 v158, v138, v139
	v_cvt_pk_bf16_f32 v159, v140, v141
	global_store_dwordx4 v212, v[156:159], s[100:101]
	v_lshlrev_b32_e32 v160, 16, v176
	v_and_b32_e32 v161, 0xffff0000, v176
	v_lshlrev_b32_e32 v174, 16, v177
	v_and_b32_e32 v175, 0xffff0000, v177
	v_lshlrev_b32_e32 v204, 16, v178
	v_and_b32_e32 v205, 0xffff0000, v178
	v_lshlrev_b32_e32 v210, 16, v179
	v_and_b32_e32 v211, 0xffff0000, v179
	v_pk_fma_f32 v[134:135], v[134:135], v[52:53], v[160:161]
	v_pk_fma_f32 v[136:137], v[136:137], v[54:55], v[174:175]
	v_pk_fma_f32 v[130:131], v[130:131], v[48:49], v[204:205]
	v_pk_fma_f32 v[132:133], v[132:133], v[50:51], v[210:211]
	v_cvt_pk_bf16_f32 v176, v134, v135
	v_cvt_pk_bf16_f32 v177, v136, v137
	v_cvt_pk_bf16_f32 v178, v130, v131
	v_cvt_pk_bf16_f32 v179, v132, v133
	global_store_dwordx4 v212, v[176:179], s[100:101] offset:256
	s_add_u32 s100, s100, 0x8000
	s_addc_u32 s101, s101, 0
	global_load_dwordx4 v[156:159], v212, s[98:99] nt
	global_load_dwordx4 v[176:179], v212, s[98:99] offset:256 nt
	s_add_u32 s98, s98, 0x8000
	s_addc_u32 s99, s99, 0
	s_waitcnt vmcnt(10)
	v_lshlrev_b32_e32 v160, 16, v180
	v_and_b32_e32 v161, 0xffff0000, v180
	v_lshlrev_b32_e32 v174, 16, v181
	v_and_b32_e32 v175, 0xffff0000, v181
	v_lshlrev_b32_e32 v204, 16, v182
	v_and_b32_e32 v205, 0xffff0000, v182
	v_lshlrev_b32_e32 v210, 16, v183
	v_and_b32_e32 v211, 0xffff0000, v183
	v_pk_fma_f32 v[126:127], v[126:127], v[60:61], v[160:161]
	v_pk_fma_f32 v[128:129], v[128:129], v[62:63], v[174:175]
	v_pk_fma_f32 v[122:123], v[122:123], v[56:57], v[204:205]
	v_pk_fma_f32 v[124:125], v[124:125], v[58:59], v[210:211]
	v_cvt_pk_bf16_f32 v180, v126, v127
	v_cvt_pk_bf16_f32 v181, v128, v129
	v_cvt_pk_bf16_f32 v182, v122, v123
	v_cvt_pk_bf16_f32 v183, v124, v125
	global_store_dwordx4 v212, v[180:183], s[100:101]
	v_lshlrev_b32_e32 v160, 16, v184
	v_and_b32_e32 v161, 0xffff0000, v184
	v_lshlrev_b32_e32 v174, 16, v185
	v_and_b32_e32 v175, 0xffff0000, v185
	v_lshlrev_b32_e32 v204, 16, v186
	v_and_b32_e32 v205, 0xffff0000, v186
	v_lshlrev_b32_e32 v210, 16, v187
	v_and_b32_e32 v211, 0xffff0000, v187
	v_pk_fma_f32 v[118:119], v[118:119], v[52:53], v[160:161]
	v_pk_fma_f32 v[120:121], v[120:121], v[54:55], v[174:175]
	v_pk_fma_f32 v[114:115], v[114:115], v[48:49], v[204:205]
	v_pk_fma_f32 v[116:117], v[116:117], v[50:51], v[210:211]
	v_cvt_pk_bf16_f32 v184, v118, v119
	v_cvt_pk_bf16_f32 v185, v120, v121
	v_cvt_pk_bf16_f32 v186, v114, v115
	v_cvt_pk_bf16_f32 v187, v116, v117
	global_store_dwordx4 v212, v[184:187], s[100:101] offset:256
	s_add_u32 s100, s100, 0x8000
	s_addc_u32 s101, s101, 0
	global_load_dwordx4 v[180:183], v212, s[98:99] nt
	global_load_dwordx4 v[184:187], v212, s[98:99] offset:256 nt
	s_add_u32 s98, s98, 0x8000
	s_addc_u32 s99, s99, 0
	s_waitcnt vmcnt(12)
; __device__ __forceinline__ unsigned cvt_pk_bf16(float lo, float hi) { f32x2_cv v = {lo, hi}; bf16x2_cv b = __builtin_convertvector(v, bf16x2_cv); return __builtin_bit_cast(unsigned, b); }
;     __device__ __forceinline__ void operator()(const f32x4 (&acc)[2][2][4][2], const Unit& u, int wr, int wc, int fr, int fq) const {
;     ...
;         for (int g = 0; g < 8; ++g) { const int ai = g >> 2, m = g & 3; const size_t off = (size_t)(row0 + ai * HALF + m * 16) * 1024 + col0;
;             if (g + 1 < 8) { const int ai2 = (g + 1) >> 2, m2 = (g + 1) & 3; load_x(xv[(g + 1) & 1], (size_t)(row0 + ai2 * HALF + m2 * 16) * 1024 + col0); }
;             float rs_ = 1.0f; if constexpr (ROWSCALE) rs_ = tab[((u.pm == pm0 ? 0 : 256) + ai * HALF + wr * 64 + m * 16 + fr) * 2 + 1];
; #pragma unroll
;             for (int bj = 0; bj < 2; ++bj) { const f32x4 v0 = xv[g & 1][bj][0] + gv[bj][0] * (acc[ai][bj][m][0] * rs_), v1 = xv[g & 1][bj][1] + gv[bj][1] * (acc[ai][bj][m][1] * rs_);
;                 u32x4 w; w.x = cvt_pk_bf16(v0[0], v0[1]); w.y = cvt_pk_bf16(v0[2], v0[3]); w.z = cvt_pk_bf16(v1[0], v1[1]); w.w = cvt_pk_bf16(v1[2], v1[3]);
;                 *(u32x4*)(out + off + bj * HALF) = w; } }
	v_lshlrev_b32_e32 v160, 16, v188
	v_and_b32_e32 v161, 0xffff0000, v188
	v_lshlrev_b32_e32 v174, 16, v189
	v_and_b32_e32 v175, 0xffff0000, v189
	v_lshlrev_b32_e32 v204, 16, v190
	v_and_b32_e32 v205, 0xffff0000, v190
	v_lshlrev_b32_e32 v210, 16, v191
	v_and_b32_e32 v211, 0xffff0000, v191
	v_pk_fma_f32 v[110:111], v[110:111], v[60:61], v[160:161]
	v_pk_fma_f32 v[112:113], v[112:113], v[62:63], v[174:175]
	v_pk_fma_f32 v[106:107], v[106:107], v[56:57], v[204:205]
	v_pk_fma_f32 v[108:109], v[108:109], v[58:59], v[210:211]
	v_cvt_pk_bf16_f32 v188, v110, v111
	v_cvt_pk_bf16_f32 v189, v112, v113
	v_cvt_pk_bf16_f32 v190, v106, v107
	v_cvt_pk_bf16_f32 v191, v108, v109
	global_store_dwordx4 v212, v[188:191], s[100:101]
	v_lshlrev_b32_e32 v160, 16, v196
	v_and_b32_e32 v161, 0xffff0000, v196
	v_lshlrev_b32_e32 v174, 16, v197
	v_and_b32_e32 v175, 0xffff0000, v197
	v_lshlrev_b32_e32 v204, 16, v198
	v_and_b32_e32 v205, 0xffff0000, v198
	v_lshlrev_b32_e32 v210, 16, v199
	v_and_b32_e32 v211, 0xffff0000, v199
	v_pk_fma_f32 v[102:103], v[102:103], v[52:53], v[160:161]
	v_pk_fma_f32 v[104:105], v[104:105], v[54:55], v[174:175]
	v_pk_fma_f32 v[98:99], v[98:99], v[48:49], v[204:205]
	v_pk_fma_f32 v[100:101], v[100:101], v[50:51], v[210:211]
	v_cvt_pk_bf16_f32 v196, v102, v103
	v_cvt_pk_bf16_f32 v197, v104, v105
	v_cvt_pk_bf16_f32 v198, v98, v99
	v_cvt_pk_bf16_f32 v199, v100, v101
	global_store_dwordx4 v212, v[196:199], s[100:101] offset:256
	s_add_u32 s100, s100, 0x8000
	s_addc_u32 s101, s101, 0
	global_load_dwordx4 v[188:191], v212, s[98:99] nt
	global_load_dwordx4 v[196:199], v212, s[98:99] offset:256 nt
	s_add_u32 s98, s98, 0x8000
	s_addc_u32 s99, s99, 0
	s_waitcnt vmcnt(14)
	v_lshlrev_b32_e32 v160, 16, v200
	v_and_b32_e32 v161, 0xffff0000, v200
	v_lshlrev_b32_e32 v174, 16, v201
	v_and_b32_e32 v175, 0xffff0000, v201
	v_lshlrev_b32_e32 v204, 16, v202
	v_and_b32_e32 v205, 0xffff0000, v202
	v_lshlrev_b32_e32 v210, 16, v203
	v_and_b32_e32 v211, 0xffff0000, v203
	v_pk_fma_f32 v[94:95], v[94:95], v[60:61], v[160:161]
	v_pk_fma_f32 v[96:97], v[96:97], v[62:63], v[174:175]
	v_pk_fma_f32 v[90:91], v[90:91], v[56:57], v[204:205]
	v_pk_fma_f32 v[92:93], v[92:93], v[58:59], v[210:211]
	v_cvt_pk_bf16_f32 v200, v94, v95
	v_cvt_pk_bf16_f32 v201, v96, v97
	v_cvt_pk_bf16_f32 v202, v90, v91
	v_cvt_pk_bf16_f32 v203, v92, v93
	global_store_dwordx4 v212, v[200:203], s[100:101]
	v_lshlrev_b32_e32 v160, 16, v224
	v_and_b32_e32 v161, 0xffff0000, v224
	v_lshlrev_b32_e32 v174, 16, v225
	v_and_b32_e32 v175, 0xffff0000, v225
	v_lshlrev_b32_e32 v204, 16, v226
	v_and_b32_e32 v205, 0xffff0000, v226
	v_lshlrev_b32_e32 v210, 16, v227
	v_and_b32_e32 v211, 0xffff0000, v227
	v_pk_fma_f32 v[86:87], v[86:87], v[52:53], v[160:161]
	v_pk_fma_f32 v[88:89], v[88:89], v[54:55], v[174:175]
	v_pk_fma_f32 v[82:83], v[82:83], v[48:49], v[204:205]
	v_pk_fma_f32 v[84:85], v[84:85], v[50:51], v[210:211]
	v_cvt_pk_bf16_f32 v224, v86, v87
	v_cvt_pk_bf16_f32 v225, v88, v89
	v_cvt_pk_bf16_f32 v226, v82, v83
	v_cvt_pk_bf16_f32 v227, v84, v85
	global_store_dwordx4 v212, v[224:227], s[100:101] offset:256
	s_add_u32 s100, s100, 0x28000
	s_addc_u32 s101, s101, 0
	s_waitcnt vmcnt(14)
	v_lshlrev_b32_e32 v160, 16, v228
	v_and_b32_e32 v161, 0xffff0000, v228
	v_lshlrev_b32_e32 v174, 16, v229
	v_and_b32_e32 v175, 0xffff0000, v229
	v_lshlrev_b32_e32 v204, 16, v230
	v_and_b32_e32 v205, 0xffff0000, v230
	v_lshlrev_b32_e32 v210, 16, v231
	v_and_b32_e32 v211, 0xffff0000, v231
	v_pk_fma_f32 v[76:77], v[76:77], v[60:61], v[160:161]
	v_pk_fma_f32 v[78:79], v[78:79], v[62:63], v[174:175]
	v_pk_fma_f32 v[72:73], v[72:73], v[56:57], v[204:205]
	v_pk_fma_f32 v[74:75], v[74:75], v[58:59], v[210:211]
	v_cvt_pk_bf16_f32 v228, v76, v77
	v_cvt_pk_bf16_f32 v229, v78, v79
	v_cvt_pk_bf16_f32 v230, v72, v73
	v_cvt_pk_bf16_f32 v231, v74, v75
	global_store_dwordx4 v212, v[228:231], s[100:101]
	v_lshlrev_b32_e32 v160, 16, v232
	v_and_b32_e32 v161, 0xffff0000, v232
	v_lshlrev_b32_e32 v174, 16, v233
	v_and_b32_e32 v175, 0xffff0000, v233
	v_lshlrev_b32_e32 v204, 16, v234
	v_and_b32_e32 v205, 0xffff0000, v234
	v_lshlrev_b32_e32 v210, 16, v235
	v_and_b32_e32 v211, 0xffff0000, v235
	v_pk_fma_f32 v[68:69], v[68:69], v[52:53], v[160:161]
	v_pk_fma_f32 v[70:71], v[70:71], v[54:55], v[174:175]
	v_pk_fma_f32 v[64:65], v[64:65], v[48:49], v[204:205]
	v_pk_fma_f32 v[66:67], v[66:67], v[50:51], v[210:211]
	v_cvt_pk_bf16_f32 v232, v68, v69
	v_cvt_pk_bf16_f32 v233, v70, v71
	v_cvt_pk_bf16_f32 v234, v64, v65
	v_cvt_pk_bf16_f32 v235, v66, v67
	global_store_dwordx4 v212, v[232:235], s[100:101] offset:256
	s_add_u32 s100, s100, 0x8000
	s_addc_u32 s101, s101, 0
	s_waitcnt vmcnt(12)
; __device__ __forceinline__ unsigned cvt_pk_bf16(float lo, float hi) { f32x2_cv v = {lo, hi}; bf16x2_cv b = __builtin_convertvector(v, bf16x2_cv); return __builtin_bit_cast(unsigned, b); }
;     __device__ __forceinline__ void operator()(const f32x4 (&acc)[2][2][4][2], const Unit& u, int wr, int wc, int fr, int fq) const {
;     ...
;         for (int g = 0; g < 8; ++g) { const int ai = g >> 2, m = g & 3; const size_t off = (size_t)(row0 + ai * HALF + m * 16) * 1024 + col0;
;             if (g + 1 < 8) { const int ai2 = (g + 1) >> 2, m2 = (g + 1) & 3; load_x(xv[(g + 1) & 1], (size_t)(row0 + ai2 * HALF + m2 * 16) * 1024 + col0); }
;             float rs_ = 1.0f; if constexpr (ROWSCALE) rs_ = tab[((u.pm == pm0 ? 0 : 256) + ai * HALF + wr * 64 + m * 16 + fr) * 2 + 1];
; #pragma unroll
;             for (int bj = 0; bj < 2; ++bj) { const f32x4 v0 = xv[g & 1][bj][0] + gv[bj][0] * (acc[ai][bj][m][0] * rs_), v1 = xv[g & 1][bj][1] + gv[bj][1] * (acc[ai][bj][m][1] * rs_);
;                 u32x4 w; w.x = cvt_pk_bf16(v0[0], v0[1]); w.y = cvt_pk_bf16(v0[2], v0[3]); w.z = cvt_pk_bf16(v1[0], v1[1]); w.w = cvt_pk_bf16(v1[2], v1[3]);
;                 *(u32x4*)(out + off + bj * HALF) = w; } }
	v_lshlrev_b32_e32 v160, 16, v156
	v_and_b32_e32 v161, 0xffff0000, v156
	v_lshlrev_b32_e32 v174, 16, v157
	v_and_b32_e32 v175, 0xffff0000, v157
	v_lshlrev_b32_e32 v204, 16, v158
	v_and_b32_e32 v205, 0xffff0000, v158
	v_lshlrev_b32_e32 v210, 16, v159
	v_and_b32_e32 v211, 0xffff0000, v159
	v_pk_fma_f32 v[44:45], v[44:45], v[60:61], v[160:161]
	v_pk_fma_f32 v[46:47], v[46:47], v[62:63], v[174:175]
	v_pk_fma_f32 v[40:41], v[40:41], v[56:57], v[204:205]
	v_pk_fma_f32 v[42:43], v[42:43], v[58:59], v[210:211]
	v_cvt_pk_bf16_f32 v156, v44, v45
	v_cvt_pk_bf16_f32 v157, v46, v47
	v_cvt_pk_bf16_f32 v158, v40, v41
	v_cvt_pk_bf16_f32 v159, v42, v43
	global_store_dwordx4 v212, v[156:159], s[100:101]
	v_lshlrev_b32_e32 v160, 16, v176
	v_and_b32_e32 v161, 0xffff0000, v176
	v_lshlrev_b32_e32 v174, 16, v177
	v_and_b32_e32 v175, 0xffff0000, v177
	v_lshlrev_b32_e32 v204, 16, v178
	v_and_b32_e32 v205, 0xffff0000, v178
	v_lshlrev_b32_e32 v210, 16, v179
	v_and_b32_e32 v211, 0xffff0000, v179
	v_pk_fma_f32 v[36:37], v[36:37], v[52:53], v[160:161]
	v_pk_fma_f32 v[38:39], v[38:39], v[54:55], v[174:175]
	v_pk_fma_f32 v[32:33], v[32:33], v[48:49], v[204:205]
	v_pk_fma_f32 v[34:35], v[34:35], v[50:51], v[210:211]
	v_cvt_pk_bf16_f32 v176, v36, v37
	v_cvt_pk_bf16_f32 v177, v38, v39
	v_cvt_pk_bf16_f32 v178, v32, v33
	v_cvt_pk_bf16_f32 v179, v34, v35
	global_store_dwordx4 v212, v[176:179], s[100:101] offset:256
	s_add_u32 s100, s100, 0x8000
	s_addc_u32 s101, s101, 0
	s_waitcnt vmcnt(10)
	v_lshlrev_b32_e32 v160, 16, v180
	v_and_b32_e32 v161, 0xffff0000, v180
	v_lshlrev_b32_e32 v174, 16, v181
	v_and_b32_e32 v175, 0xffff0000, v181
	v_lshlrev_b32_e32 v204, 16, v182
	v_and_b32_e32 v205, 0xffff0000, v182
	v_lshlrev_b32_e32 v210, 16, v183
	v_and_b32_e32 v211, 0xffff0000, v183
	v_pk_fma_f32 v[28:29], v[28:29], v[60:61], v[160:161]
	v_pk_fma_f32 v[30:31], v[30:31], v[62:63], v[174:175]
	v_pk_fma_f32 v[24:25], v[24:25], v[56:57], v[204:205]
	v_pk_fma_f32 v[26:27], v[26:27], v[58:59], v[210:211]
	v_cvt_pk_bf16_f32 v180, v28, v29
	v_cvt_pk_bf16_f32 v181, v30, v31
	v_cvt_pk_bf16_f32 v182, v24, v25
	v_cvt_pk_bf16_f32 v183, v26, v27
	global_store_dwordx4 v212, v[180:183], s[100:101]
	v_lshlrev_b32_e32 v160, 16, v184
	v_and_b32_e32 v161, 0xffff0000, v184
	v_lshlrev_b32_e32 v174, 16, v185
	v_and_b32_e32 v175, 0xffff0000, v185
	v_lshlrev_b32_e32 v204, 16, v186
	v_and_b32_e32 v205, 0xffff0000, v186
	v_lshlrev_b32_e32 v210, 16, v187
	v_and_b32_e32 v211, 0xffff0000, v187
	v_pk_fma_f32 v[20:21], v[20:21], v[52:53], v[160:161]
	v_pk_fma_f32 v[22:23], v[22:23], v[54:55], v[174:175]
	v_pk_fma_f32 v[16:17], v[16:17], v[48:49], v[204:205]
	v_pk_fma_f32 v[18:19], v[18:19], v[50:51], v[210:211]
	v_cvt_pk_bf16_f32 v184, v20, v21
	v_cvt_pk_bf16_f32 v185, v22, v23
	v_cvt_pk_bf16_f32 v186, v16, v17
	v_cvt_pk_bf16_f32 v187, v18, v19
	global_store_dwordx4 v212, v[184:187], s[100:101] offset:256
	s_add_u32 s100, s100, 0x8000
	s_addc_u32 s101, s101, 0
	s_waitcnt vmcnt(8)
	v_lshlrev_b32_e32 v160, 16, v188
	v_and_b32_e32 v161, 0xffff0000, v188
	v_lshlrev_b32_e32 v174, 16, v189
	v_and_b32_e32 v175, 0xffff0000, v189
	v_lshlrev_b32_e32 v204, 16, v190
	v_and_b32_e32 v205, 0xffff0000, v190
	v_lshlrev_b32_e32 v210, 16, v191
	v_and_b32_e32 v211, 0xffff0000, v191
	v_pk_fma_f32 v[12:13], v[12:13], v[60:61], v[160:161]
	v_pk_fma_f32 v[14:15], v[14:15], v[62:63], v[174:175]
	v_pk_fma_f32 v[8:9], v[8:9], v[56:57], v[204:205]
	v_pk_fma_f32 v[10:11], v[10:11], v[58:59], v[210:211]
	v_cvt_pk_bf16_f32 v188, v12, v13
	v_cvt_pk_bf16_f32 v189, v14, v15
	v_cvt_pk_bf16_f32 v190, v8, v9
	v_cvt_pk_bf16_f32 v191, v10, v11
	global_store_dwordx4 v212, v[188:191], s[100:101]
	v_lshlrev_b32_e32 v160, 16, v196
	v_and_b32_e32 v161, 0xffff0000, v196
	v_lshlrev_b32_e32 v174, 16, v197
	v_and_b32_e32 v175, 0xffff0000, v197
	v_lshlrev_b32_e32 v204, 16, v198
	v_and_b32_e32 v205, 0xffff0000, v198
	v_lshlrev_b32_e32 v210, 16, v199
	v_and_b32_e32 v211, 0xffff0000, v199
	v_pk_fma_f32 v[4:5], v[4:5], v[52:53], v[160:161]
	v_pk_fma_f32 v[6:7], v[6:7], v[54:55], v[174:175]
	v_pk_fma_f32 v[0:1], v[0:1], v[48:49], v[204:205]
	v_pk_fma_f32 v[2:3], v[2:3], v[50:51], v[210:211]
	v_cvt_pk_bf16_f32 v196, v4, v5
	v_cvt_pk_bf16_f32 v197, v6, v7
	v_cvt_pk_bf16_f32 v198, v0, v1
	v_cvt_pk_bf16_f32 v199, v2, v3
	global_store_dwordx4 v212, v[196:199], s[100:101] offset:256
	s_add_u32 s100, s100, 0x8000
	s_addc_u32 s101, s101, 0
	s_mov_b64 s[4:5], -1
	s_and_b64 vcc, exec, s[36:37]
	s_cbranch_vccnz .LBB0_693
	s_andn2_b64 vcc, exec, s[14:15]
	s_cbranch_vccnz .LBB0_692
	s_barrier
	s_branch .LBB0_692

; __device__ __forceinline__ void unpack8(const u32x4 w, f32x4& a, f32x4& c) { a = (f32x4){bf_lo(w.x), bf_hi(w.x), bf_lo(w.y), bf_hi(w.y)}; c = (f32x4){bf_lo(w.z), bf_hi(w.z), bf_lo(w.w), bf_hi(w.w)}; }
; __device__ __forceinline__ void phase_final(const Ctx& C) {
;     ...
;     for (int r0_ = (gw % (NGW >> 3)) * NRW; r0_ < T / 8; r0_ += (NGW >> 3) * NRW) { const int m0 = (gw / (NGW >> 3)) * (T / 8) + r0_;
;         f32x4 v[NRW][4]; float s[NRW];
; #pragma unroll
;         for (int r = 0; r < NRW; ++r) { s[r] = 0.f;
; #pragma unroll
;             for (int j = 0; j < 2; ++j) { unpack8(((const u32x4*)(XR + (size_t)(m0 + r) * DM + 512 * j))[lane], v[r][2 * j], v[r][2 * j + 1]);
; #pragma unroll
;                 for (int q = 0; q < 2; ++q) { const f32x4 t = v[r][2 * j + q]; s[r] += (t.x * t.x + t.y * t.y) + (t.z * t.z + t.w * t.w); } } }
.LBB0_761:
	s_add_i32 s0, s13, s15
	s_ashr_i32 s1, s0, 31
	s_add_i32 s2, s0, 1
	s_lshl_b64 s[8:9], s[0:1], 11
	s_add_i32 s4, s0, 2
	s_add_i32 s6, s0, 3
	s_ashr_i32 s3, s2, 31
	v_lshl_add_u64 v[20:21], v[16:17], 0, s[8:9]
	s_ashr_i32 s5, s4, 31
	s_ashr_i32 s7, s6, 31
	s_lshl_b64 s[8:9], s[2:3], 11
	flat_load_dwordx4 v[28:31], v[20:21] nt
	flat_load_dwordx4 v[32:35], v[20:21] offset:1024 nt
	s_lshl_b64 s[10:11], s[4:5], 11
	s_lshl_b64 s[18:19], s[6:7], 11
	v_lshl_add_u64 v[52:53], v[16:17], 0, s[8:9]
	v_lshl_add_u64 v[54:55], v[16:17], 0, s[10:11]
	v_lshl_add_u64 v[56:57], v[16:17], 0, s[18:19]
	flat_load_dwordx4 v[36:39], v[52:53] nt
	flat_load_dwordx4 v[40:43], v[52:53] offset:1024 nt
	flat_load_dwordx4 v[44:47], v[54:55] nt
	flat_load_dwordx4 v[48:51], v[54:55] offset:1024 nt
	flat_load_dwordx4 v[84:87], v[56:57] nt
	flat_load_dwordx4 v[88:91], v[56:57] offset:1024 nt
	s_lshl_b64 s[0:1], s[0:1], 12
	v_lshl_add_u64 v[26:27], v[18:19], 0, s[0:1]
	s_lshl_b64 s[0:1], s[2:3], 12
	s_lshl_b64 s[2:3], s[4:5], 12
	s_lshl_b64 s[4:5], s[6:7], 12
	v_lshl_add_u64 v[24:25], v[18:19], 0, s[0:1]
	v_lshl_add_u64 v[22:23], v[18:19], 0, s[2:3]
	v_lshl_add_u64 v[20:21], v[18:19], 0, s[4:5]
	s_add_i32 s14, s14, s12
	s_add_i32 s15, s15, s12
	s_add_i32 s17, s13, s14
	s_cmpk_lt_i32 s17, 0x1000
	s_waitcnt vmcnt(0) lgkmcnt(0)
	v_lshlrev_b32_e32 v52, 16, v28
	v_lshlrev_b32_e32 v54, 16, v29
	v_and_b32_e32 v61, 0xffff0000, v31
	v_and_b32_e32 v60, 0xffff0000, v30
	v_lshlrev_b32_e32 v76, 16, v32
	v_lshlrev_b32_e32 v78, 16, v33
	v_and_b32_e32 v53, 0xffff0000, v28
	v_and_b32_e32 v55, 0xffff0000, v29
	v_lshlrev_b32_e32 v101, 16, v31
	v_lshlrev_b32_e32 v100, 16, v30
	v_and_b32_e32 v77, 0xffff0000, v32
	v_and_b32_e32 v79, 0xffff0000, v33
	v_mul_f32_e32 v102, v52, v52
	v_mul_f32_e32 v104, v54, v54
	v_pk_mul_f32 v[106:107], v[60:61], v[60:61]
	v_mul_f32_e32 v108, v76, v76
	v_mul_f32_e32 v110, v78, v78
	v_lshlrev_b32_e32 v62, 16, v36
	v_and_b32_e32 v63, 0xffff0000, v36
	v_lshlrev_b32_e32 v66, 16, v37
	v_and_b32_e32 v67, 0xffff0000, v37
	v_lshlrev_b32_e32 v114, 16, v38
	v_and_b32_e32 v75, 0xffff0000, v39
	v_and_b32_e32 v74, 0xffff0000, v38
	v_lshlrev_b32_e32 v80, 16, v40
	v_and_b32_e32 v81, 0xffff0000, v40
	v_lshlrev_b32_e32 v38, 16, v44
	v_lshlrev_b32_e32 v40, 16, v45
	v_lshlrev_b32_e32 v117, 16, v47
	v_lshlrev_b32_e32 v116, 16, v46
	v_and_b32_e32 v47, 0xffff0000, v47
	v_and_b32_e32 v46, 0xffff0000, v46
	v_and_b32_e32 v37, 0xffff0000, v87
	v_and_b32_e32 v36, 0xffff0000, v86
	v_lshlrev_b32_e32 v56, 16, v34
	v_and_b32_e32 v57, 0xffff0000, v34
	v_lshlrev_b32_e32 v58, 16, v35
	v_and_b32_e32 v59, 0xffff0000, v35
	v_lshlrev_b32_e32 v115, 16, v39
	v_lshlrev_b32_e32 v82, 16, v41
	v_and_b32_e32 v83, 0xffff0000, v41
	v_and_b32_e32 v39, 0xffff0000, v44
	v_and_b32_e32 v41, 0xffff0000, v45
	v_lshlrev_b32_e32 v64, 16, v48
	v_lshlrev_b32_e32 v70, 16, v49
	v_lshlrev_b32_e32 v28, 16, v84
	v_lshlrev_b32_e32 v30, 16, v85
	v_lshlrev_b32_e32 v119, 16, v87
	v_lshlrev_b32_e32 v118, 16, v86
	v_lshlrev_b32_e32 v32, 16, v90
	v_and_b32_e32 v33, 0xffff0000, v90
	v_lshlrev_b32_e32 v34, 16, v91
	v_and_b32_e32 v35, 0xffff0000, v91
	v_mov_b32_e32 v90, v100
	v_mov_b32_e32 v91, v60
	v_mov_b32_e32 v60, v101
	v_pk_fma_f32 v[102:103], v[52:53], v[52:53], v[102:103] op_sel_hi:[1,1,0]
	v_pk_fma_f32 v[104:105], v[54:55], v[54:55], v[104:105] op_sel_hi:[1,1,0]
	v_pk_fma_f32 v[100:101], v[100:101], v[100:101], v[106:107]
	v_pk_fma_f32 v[106:107], v[76:77], v[76:77], v[108:109] op_sel_hi:[1,1,0]
	v_pk_fma_f32 v[108:109], v[78:79], v[78:79], v[110:111] op_sel_hi:[1,1,0]
	v_mul_f32_e32 v110, v62, v62
	v_mul_f32_e32 v120, v66, v66
	v_pk_mul_f32 v[122:123], v[74:75], v[74:75]
	v_pk_mul_f32 v[126:127], v[46:47], v[46:47]
	v_pk_mul_f32 v[128:129], v[36:37], v[36:37]
	v_mul_f32_e32 v132, v38, v38
	v_mul_f32_e32 v134, v40, v40
	v_lshlrev_b32_e32 v68, 16, v42
	v_and_b32_e32 v69, 0xffff0000, v42
	v_lshlrev_b32_e32 v72, 16, v43
	v_and_b32_e32 v73, 0xffff0000, v43
	v_lshlrev_b32_e32 v42, 16, v50
	v_and_b32_e32 v43, 0xffff0000, v50
	v_lshlrev_b32_e32 v44, 16, v51
	v_and_b32_e32 v45, 0xffff0000, v51
	v_and_b32_e32 v65, 0xffff0000, v48
	v_and_b32_e32 v71, 0xffff0000, v49
	v_and_b32_e32 v29, 0xffff0000, v84
	v_and_b32_e32 v31, 0xffff0000, v85
	v_lshlrev_b32_e32 v48, 16, v88
	v_and_b32_e32 v49, 0xffff0000, v88
	v_lshlrev_b32_e32 v50, 16, v89
	v_and_b32_e32 v51, 0xffff0000, v89
	v_mul_f32_e32 v124, v80, v80
	v_mov_b32_e32 v88, v114
	v_mov_b32_e32 v89, v74
	v_mov_b32_e32 v74, v115
	v_mov_b32_e32 v86, v116
	v_mov_b32_e32 v87, v46
	v_mov_b32_e32 v46, v117
	v_mov_b32_e32 v84, v118
	v_mov_b32_e32 v85, v36
	v_mov_b32_e32 v36, v119
	v_mul_f32_e32 v130, v82, v82
	v_mul_f32_e32 v136, v28, v28
	v_mul_f32_e32 v138, v30, v30
	v_mul_f32_e32 v142, v64, v64
	v_mul_f32_e32 v144, v70, v70
	v_pk_add_f32 v[102:103], v[102:103], v[104:105]
	v_pk_fma_f32 v[104:105], v[114:115], v[114:115], v[122:123]
	v_pk_fma_f32 v[114:115], v[116:117], v[116:117], v[126:127]
	v_pk_fma_f32 v[116:117], v[118:119], v[118:119], v[128:129]
	v_mul_f32_e32 v106, v58, v58
	v_mul_f32_e32 v108, v59, v59
	v_pk_fma_f32 v[110:111], v[62:63], v[62:63], v[110:111] op_sel_hi:[1,1,0]
	v_pk_fma_f32 v[118:119], v[66:67], v[66:67], v[120:121] op_sel_hi:[1,1,0]
	v_pk_fma_f32 v[120:121], v[38:39], v[38:39], v[132:133] op_sel_hi:[1,1,0]
	v_pk_fma_f32 v[122:123], v[40:41], v[40:41], v[134:135] op_sel_hi:[1,1,0]
	v_pk_add_f32 v[100:101], v[100:101], v[100:101] op_sel_hi:[0,1]
	v_mul_f32_e32 v112, v56, v56
	v_mul_f32_e32 v148, v48, v48
	v_mul_f32_e32 v150, v50, v50
	v_pk_fma_f32 v[126:127], v[28:29], v[28:29], v[136:137] op_sel_hi:[1,1,0]
	v_pk_fma_f32 v[128:129], v[30:31], v[30:31], v[138:139] op_sel_hi:[1,1,0]
; template <int NR> __device__ __forceinline__ void wave_sumN(float (&s)[NR]) {
; #pragma unroll
;     for (int o = 1; o < 64; o <<= 1) {
;         float t[NR];
; #pragma unroll
;         for (int r = 0; r < NR; ++r) t[r] = __shfl_xor(s[r], o);
; #pragma unroll
;         for (int r = 0; r < NR; ++r) s[r] += t[r];
;     }
; }
; __device__ __forceinline__ void phase_final(const Ctx& C) {
;     ...
;                 for (int q = 0; q < 2; ++q) { const f32x4 t = v[r][2 * j + q]; s[r] += (t.x * t.x + t.y * t.y) + (t.z * t.z + t.w * t.w); } } }
;         wave_sumN<NRW>(s);
; #pragma unroll
;         for (int r = 0; r < NRW; ++r) { const float rs = 1.0f / sqrtf(s[r] * (1.f / DM) + EPS);
	v_pk_fma_f32 v[124:125], v[80:81], v[80:81], v[124:125] op_sel_hi:[1,1,0]
	v_pk_fma_f32 v[130:131], v[82:83], v[82:83], v[130:131] op_sel_hi:[1,1,0]
	v_pk_fma_f32 v[132:133], v[64:65], v[64:65], v[142:143] op_sel_hi:[1,1,0]
	v_pk_fma_f32 v[134:135], v[70:71], v[70:71], v[144:145] op_sel_hi:[1,1,0]
	v_mov_b32_e32 v113, v103
	v_pk_add_f32 v[102:103], v[106:107], v[108:109]
	v_pk_add_f32 v[106:107], v[110:111], v[118:119]
	v_pk_add_f32 v[108:109], v[120:121], v[122:123]
	v_mul_f32_e32 v100, v57, v57
	v_pk_add_f32 v[104:105], v[104:105], v[104:105] op_sel_hi:[0,1]
	v_pk_add_f32 v[114:115], v[114:115], v[114:115] op_sel_hi:[0,1]
	v_mul_f32_e32 v140, v68, v68
	v_mul_f32_e32 v146, v42, v42
	v_pk_fma_f32 v[136:137], v[48:49], v[48:49], v[148:149] op_sel_hi:[1,1,0]
	v_pk_fma_f32 v[138:139], v[50:51], v[50:51], v[150:151] op_sel_hi:[1,1,0]
	v_pk_add_f32 v[110:111], v[126:127], v[128:129]
	v_mul_f32_e32 v124, v72, v72
	v_mul_f32_e32 v130, v73, v73
	v_mul_f32_e32 v132, v44, v44
	v_mul_f32_e32 v134, v45, v45
	v_pk_add_f32 v[116:117], v[116:117], v[116:117] op_sel_hi:[0,1]
	v_pk_add_f32 v[100:101], v[112:113], v[100:101]
	v_mov_b32_e32 v141, v107
	v_mov_b32_e32 v147, v109
	v_mul_f32_e32 v104, v69, v69
	v_mul_f32_e32 v114, v43, v43
	v_mul_f32_e32 v152, v32, v32
	v_mul_f32_e32 v136, v34, v34
	v_mul_f32_e32 v138, v35, v35
	v_pk_add_f32 v[106:107], v[124:125], v[130:131]
	v_pk_add_f32 v[108:109], v[132:133], v[134:135]
	v_mov_b32_e32 v153, v111
	v_mul_f32_e32 v116, v33, v33
	v_pk_add_f32 v[100:101], v[100:101], v[102:103]
	v_pk_add_f32 v[102:103], v[140:141], v[104:105]
	v_pk_add_f32 v[104:105], v[146:147], v[114:115]
	v_pk_add_f32 v[110:111], v[136:137], v[138:139]
	v_pk_add_f32 v[112:113], v[152:153], v[116:117]
	v_add_f32_e32 v114, v100, v101
	v_pk_add_f32 v[100:101], v[102:103], v[106:107]
	v_pk_add_f32 v[102:103], v[104:105], v[108:109]
	v_pk_add_f32 v[104:105], v[112:113], v[110:111]
	v_add_f32_e32 v100, v100, v101
	v_add_f32_e32 v101, v102, v103
	ds_bpermute_b32 v103, v92, v114
	v_add_f32_e32 v102, v104, v105
	ds_bpermute_b32 v104, v92, v100
	ds_bpermute_b32 v105, v92, v101
	ds_bpermute_b32 v106, v92, v102
	s_waitcnt lgkmcnt(3)
	v_add_f32_e32 v103, v114, v103
	s_waitcnt lgkmcnt(2)
	v_add_f32_e32 v100, v100, v104
	ds_bpermute_b32 v104, v93, v103
	s_waitcnt lgkmcnt(2)
	v_add_f32_e32 v101, v101, v105
	s_waitcnt lgkmcnt(1)
	v_add_f32_e32 v102, v102, v106
	ds_bpermute_b32 v105, v93, v100
	ds_bpermute_b32 v106, v93, v101
	ds_bpermute_b32 v107, v93, v102
	s_waitcnt lgkmcnt(3)
	v_add_f32_e32 v103, v103, v104
	ds_bpermute_b32 v104, v94, v103
	s_waitcnt lgkmcnt(3)
	v_add_f32_e32 v100, v100, v105
	s_waitcnt lgkmcnt(2)
	v_add_f32_e32 v101, v101, v106
	s_waitcnt lgkmcnt(1)
	v_add_f32_e32 v102, v102, v107
	ds_bpermute_b32 v105, v94, v100
	ds_bpermute_b32 v106, v94, v101
	ds_bpermute_b32 v107, v94, v102
	s_waitcnt lgkmcnt(3)
	v_add_f32_e32 v103, v103, v104
	ds_bpermute_b32 v104, v95, v103
	s_waitcnt lgkmcnt(3)
	v_add_f32_e32 v100, v100, v105
	s_waitcnt lgkmcnt(2)
	v_add_f32_e32 v101, v101, v106
	s_waitcnt lgkmcnt(1)
	v_add_f32_e32 v102, v102, v107
	ds_bpermute_b32 v105, v95, v100
	ds_bpermute_b32 v106, v95, v101
	ds_bpermute_b32 v107, v95, v102
	s_waitcnt lgkmcnt(3)
	v_add_f32_e32 v103, v103, v104
	ds_bpermute_b32 v104, v96, v103
	s_waitcnt lgkmcnt(3)
	v_add_f32_e32 v100, v100, v105
	s_waitcnt lgkmcnt(2)
	v_add_f32_e32 v101, v101, v106
	s_waitcnt lgkmcnt(1)
	v_add_f32_e32 v102, v102, v107
	ds_bpermute_b32 v105, v96, v100
	ds_bpermute_b32 v106, v96, v101
	ds_bpermute_b32 v107, v96, v102
	s_waitcnt lgkmcnt(3)
	v_add_f32_e32 v103, v103, v104
	ds_bpermute_b32 v104, v97, v103
	s_waitcnt lgkmcnt(3)
	v_add_f32_e32 v100, v100, v105
	s_waitcnt lgkmcnt(2)
	v_add_f32_e32 v101, v101, v106
	s_waitcnt lgkmcnt(1)
	v_add_f32_e32 v102, v102, v107
	ds_bpermute_b32 v105, v97, v100
	ds_bpermute_b32 v106, v97, v101
	ds_bpermute_b32 v107, v97, v102
	s_waitcnt lgkmcnt(3)
	v_add_f32_e32 v103, v103, v104
	v_fmamk_f32 v103, v103, 0x3a800000, v98
	s_waitcnt lgkmcnt(2)
	v_add_f32_e32 v100, v100, v105
	v_mul_f32_e32 v104, 0x4f800000, v103
	v_cmp_gt_f32_e32 vcc, s16, v103
	s_waitcnt lgkmcnt(1)
	v_add_f32_e32 v101, v101, v106
	s_waitcnt lgkmcnt(0)
	v_add_f32_e32 v102, v102, v107
	v_fmamk_f32 v100, v100, 0x3a800000, v98
	v_cndmask_b32_e32 v103, v103, v104, vcc
	v_fmamk_f32 v101, v101, 0x3a800000, v98
	v_fmamk_f32 v102, v102, 0x3a800000, v98
	v_mul_f32_e32 v104, 0x4f800000, v100
	v_cmp_gt_f32_e64 s[0:1], s16, v100
	v_sqrt_f32_e32 v107, v103
	v_mul_f32_e32 v105, 0x4f800000, v101
	v_cmp_gt_f32_e64 s[2:3], s16, v101
	v_mul_f32_e32 v106, 0x4f800000, v102
	v_cmp_gt_f32_e64 s[4:5], s16, v102
	v_cndmask_b32_e64 v100, v100, v104, s[0:1]
	v_cndmask_b32_e64 v101, v101, v105, s[2:3]
	v_cndmask_b32_e64 v102, v102, v106, s[4:5]
	v_sqrt_f32_e32 v104, v100
	v_sqrt_f32_e32 v105, v101
	v_sqrt_f32_e32 v106, v102
	v_add_u32_e32 v108, -1, v107
	v_add_u32_e32 v109, 1, v107
	v_fma_f32 v110, -v108, v107, v103
	v_fma_f32 v111, -v109, v107, v103
	v_add_u32_e32 v112, -1, v104
	v_cmp_ge_f32_e64 s[6:7], 0, v110
	v_add_u32_e32 v113, 1, v104
	v_add_u32_e32 v114, -1, v105
	v_add_u32_e32 v116, -1, v106
	v_cndmask_b32_e64 v107, v107, v108, s[6:7]
	v_fma_f32 v108, -v112, v104, v100
	v_cmp_lt_f32_e64 s[6:7], 0, v111
	v_add_u32_e32 v115, 1, v105
	v_add_u32_e32 v117, 1, v106
	v_fma_f32 v110, -v113, v104, v100
	v_fma_f32 v118, -v114, v105, v101
	v_fma_f32 v120, -v116, v106, v102
	v_cndmask_b32_e64 v107, v107, v109, s[6:7]
	v_cmp_ge_f32_e64 s[6:7], 0, v108
	v_fma_f32 v119, -v115, v105, v101
	v_fma_f32 v121, -v117, v106, v102
	v_cndmask_b32_e64 v104, v104, v112, s[6:7]
	v_cmp_lt_f32_e64 s[6:7], 0, v110
	v_cmp_ge_f32_e64 s[8:9], 0, v118
; __device__ __forceinline__ void phase_final(const Ctx& C) {
;     ...
;         wave_sumN<NRW>(s);
; #pragma unroll
;         for (int r = 0; r < NRW; ++r) { const float rs = 1.0f / sqrtf(s[r] * (1.f / DM) + EPS);
; #pragma unroll
;             for (int j = 0; j < 2; ++j)
; #pragma unroll
;                 for (int q = 0; q < 2; ++q) *(f32x4*)(out_ + (size_t)(m0 + r) * DM + 512 * j + 8 * lane + 4 * q) = v[r][2 * j + q] * rs * g[2 * j + q]; }
;     }
	v_cmp_ge_f32_e64 s[10:11], 0, v120
	v_mul_f32_e32 v108, 0x37800000, v107
	v_cndmask_b32_e64 v105, v105, v114, s[8:9]
	v_cmp_lt_f32_e64 s[8:9], 0, v119
	v_cndmask_b32_e64 v106, v106, v116, s[10:11]
	v_cmp_lt_f32_e64 s[10:11], 0, v121
	v_cndmask_b32_e64 v104, v104, v113, s[6:7]
	v_cndmask_b32_e64 v105, v105, v115, s[8:9]
	v_cndmask_b32_e64 v106, v106, v117, s[10:11]
	v_cndmask_b32_e32 v107, v107, v108, vcc
	v_mul_f32_e32 v108, 0x37800000, v104
	v_cmp_class_f32_e32 vcc, v103, v99
	v_mul_f32_e32 v109, 0x37800000, v105
	v_mul_f32_e32 v110, 0x37800000, v106
	v_cndmask_b32_e32 v103, v107, v103, vcc
	v_cndmask_b32_e64 v104, v104, v108, s[0:1]
	v_cmp_class_f32_e32 vcc, v100, v99
	v_cndmask_b32_e64 v105, v105, v109, s[2:3]
	v_cmp_class_f32_e64 s[0:1], v101, v99
	v_cndmask_b32_e64 v106, v106, v110, s[4:5]
	v_div_scale_f32 v107, s[4:5], v103, v103, 1.0
	v_cndmask_b32_e32 v109, v104, v100, vcc
	v_cmp_class_f32_e64 s[2:3], v102, v99
	v_cndmask_b32_e64 v110, v105, v101, s[0:1]
	v_rcp_f32_e32 v100, v107
	v_div_scale_f32 v101, s[0:1], v109, v109, 1.0
	v_cndmask_b32_e64 v111, v106, v102, s[2:3]
	v_div_scale_f32 v104, s[2:3], v110, v110, 1.0
	v_rcp_f32_e32 v113, v101
	v_div_scale_f32 v106, s[6:7], v111, v111, 1.0
	v_rcp_f32_e32 v114, v104
	v_rcp_f32_e32 v115, v106
	v_fma_f32 v116, -v107, v100, 1.0
	v_div_scale_f32 v108, s[4:5], 1.0, v103, 1.0
	v_fmac_f32_e32 v100, v116, v100
	v_fma_f32 v116, -v101, v113, 1.0
	v_div_scale_f32 v102, s[0:1], 1.0, v109, 1.0
	v_fma_f32 v117, -v104, v114, 1.0
	v_mul_f32_e32 v119, v108, v100
	v_fmac_f32_e32 v113, v116, v113
	v_div_scale_f32 v105, s[2:3], 1.0, v110, 1.0
	v_fma_f32 v118, -v106, v115, 1.0
	v_fmac_f32_e32 v114, v117, v114
	v_fma_f32 v116, -v107, v119, v108
	v_mul_f32_e32 v117, v102, v113
	v_div_scale_f32 v112, s[6:7], 1.0, v111, 1.0
	v_fmac_f32_e32 v115, v118, v115
	v_mul_f32_e32 v118, v105, v114
	v_fmac_f32_e32 v119, v116, v100
	v_fma_f32 v116, -v101, v117, v102
	v_mul_f32_e32 v120, v112, v115
	v_fma_f32 v121, -v104, v118, v105
	v_fma_f32 v107, -v107, v119, v108
	v_fmac_f32_e32 v117, v116, v113
	s_mov_b64 vcc, s[4:5]
	v_fma_f32 v122, -v106, v120, v112
	v_fmac_f32_e32 v118, v121, v114
	v_div_fmas_f32 v100, v107, v100, v119
	v_fma_f32 v101, -v101, v117, v102
	s_mov_b64 vcc, s[0:1]
	v_fmac_f32_e32 v120, v122, v115
	v_fma_f32 v102, -v104, v118, v105
	v_div_fixup_f32 v100, v100, v103, 1.0
	v_div_fmas_f32 v103, v101, v113, v117
	s_mov_b64 vcc, s[2:3]
	v_fma_f32 v107, -v106, v120, v112
	v_pk_mul_f32 v[52:53], v[100:101], v[52:53] op_sel_hi:[0,1]
	v_pk_mul_f32 v[54:55], v[100:101], v[54:55] op_sel_hi:[0,1]
	v_pk_mul_f32 v[90:91], v[100:101], v[90:91] op_sel_hi:[0,1]
	v_pk_mul_f32 v[60:61], v[100:101], v[60:61] op_sel_hi:[0,1]
	v_pk_mul_f32 v[76:77], v[100:101], v[76:77] op_sel_hi:[0,1]
	v_div_fixup_f32 v106, v103, v109, 1.0
	v_div_fmas_f32 v108, v102, v114, v118
	s_mov_b64 vcc, s[6:7]
	v_pk_mul_f32 v[78:79], v[100:101], v[78:79] op_sel_hi:[0,1]
	v_pk_mul_f32 v[104:105], v[100:101], v[56:57] op_sel_hi:[0,1]
	v_pk_mul_f32 v[100:101], v[100:101], v[58:59] op_sel_hi:[0,1]
	v_pk_mul_f32 v[54:55], v[6:7], v[54:55]
	v_pk_mul_f32 v[52:53], v[4:5], v[52:53]
	v_pk_mul_f32 v[58:59], v[2:3], v[60:61]
	v_pk_mul_f32 v[56:57], v[0:1], v[90:91]
	v_pk_mul_f32 v[76:77], v[12:13], v[76:77]
	v_pk_mul_f32 v[60:61], v[106:107], v[62:63] op_sel_hi:[0,1]
	v_pk_mul_f32 v[62:63], v[106:107], v[66:67] op_sel_hi:[0,1]
	v_pk_mul_f32 v[66:67], v[106:107], v[88:89] op_sel_hi:[0,1]
	v_pk_mul_f32 v[88:89], v[106:107], v[68:69] op_sel_hi:[0,1]
	v_pk_mul_f32 v[68:69], v[106:107], v[72:73] op_sel_hi:[0,1]
	v_div_fixup_f32 v72, v108, v110, 1.0
	v_div_fmas_f32 v90, v107, v115, v120
	v_pk_mul_f32 v[78:79], v[14:15], v[78:79]
	v_pk_mul_f32 v[102:103], v[10:11], v[100:101]
	v_pk_mul_f32 v[100:101], v[8:9], v[104:105]
	v_pk_mul_f32 v[74:75], v[106:107], v[74:75] op_sel_hi:[0,1]
	v_pk_mul_f32 v[80:81], v[106:107], v[80:81] op_sel_hi:[0,1]
	v_pk_mul_f32 v[82:83], v[106:107], v[82:83] op_sel_hi:[0,1]
	flat_store_dwordx4 v[26:27], v[52:55] nt
	flat_store_dwordx4 v[26:27], v[56:59] offset:16 nt
	flat_store_dwordx4 v[26:27], v[76:79] offset:2048 nt
	flat_store_dwordx4 v[26:27], v[100:103] offset:2064 nt
	v_pk_mul_f32 v[54:55], v[6:7], v[62:63]
	v_pk_mul_f32 v[52:53], v[4:5], v[60:61]
	v_pk_mul_f32 v[38:39], v[72:73], v[38:39] op_sel_hi:[0,1]
	v_pk_mul_f32 v[26:27], v[72:73], v[40:41] op_sel_hi:[0,1]
	v_div_fixup_f32 v76, v90, v111, 1.0
	v_pk_mul_f32 v[58:59], v[2:3], v[74:75]
	v_pk_mul_f32 v[56:57], v[0:1], v[66:67]
	v_pk_mul_f32 v[62:63], v[14:15], v[82:83]
	v_pk_mul_f32 v[60:61], v[12:13], v[80:81]
	v_pk_mul_f32 v[68:69], v[10:11], v[68:69]
	v_pk_mul_f32 v[66:67], v[8:9], v[88:89]
	v_pk_mul_f32 v[74:75], v[72:73], v[86:87] op_sel_hi:[0,1]
	v_pk_mul_f32 v[40:41], v[72:73], v[46:47] op_sel_hi:[0,1]
	v_pk_mul_f32 v[46:47], v[72:73], v[64:65] op_sel_hi:[0,1]
	v_pk_mul_f32 v[64:65], v[72:73], v[70:71] op_sel_hi:[0,1]
	v_pk_mul_f32 v[70:71], v[72:73], v[42:43] op_sel_hi:[0,1]
	v_pk_mul_f32 v[72:73], v[72:73], v[44:45] op_sel_hi:[0,1]
	flat_store_dwordx4 v[24:25], v[52:55] nt
	flat_store_dwordx4 v[24:25], v[56:59] offset:16 nt
	flat_store_dwordx4 v[24:25], v[60:63] offset:2048 nt
	flat_store_dwordx4 v[24:25], v[66:69] offset:2064 nt
	v_pk_mul_f32 v[26:27], v[6:7], v[26:27]
	v_pk_mul_f32 v[24:25], v[4:5], v[38:39]
	v_pk_mul_f32 v[28:29], v[76:77], v[28:29] op_sel_hi:[0,1]
	v_pk_mul_f32 v[30:31], v[76:77], v[30:31] op_sel_hi:[0,1]
	v_pk_mul_f32 v[40:41], v[2:3], v[40:41]
	v_pk_mul_f32 v[38:39], v[0:1], v[74:75]
	v_pk_mul_f32 v[44:45], v[14:15], v[64:65]
	v_pk_mul_f32 v[42:43], v[12:13], v[46:47]
	v_pk_mul_f32 v[54:55], v[10:11], v[72:73]
	v_pk_mul_f32 v[52:53], v[8:9], v[70:71]
	v_pk_mul_f32 v[46:47], v[76:77], v[84:85] op_sel_hi:[0,1]
	v_pk_mul_f32 v[36:37], v[76:77], v[36:37] op_sel_hi:[0,1]
	v_pk_mul_f32 v[48:49], v[76:77], v[48:49] op_sel_hi:[0,1]
	v_pk_mul_f32 v[50:51], v[76:77], v[50:51] op_sel_hi:[0,1]
	v_pk_mul_f32 v[56:57], v[76:77], v[32:33] op_sel_hi:[0,1]
	v_pk_mul_f32 v[34:35], v[76:77], v[34:35] op_sel_hi:[0,1]
	flat_store_dwordx4 v[22:23], v[24:27] nt
	flat_store_dwordx4 v[22:23], v[38:41] offset:16 nt
	flat_store_dwordx4 v[22:23], v[42:45] offset:2048 nt
	flat_store_dwordx4 v[22:23], v[52:55] offset:2064 nt
	v_pk_mul_f32 v[24:25], v[6:7], v[30:31]
	v_pk_mul_f32 v[22:23], v[4:5], v[28:29]
	v_pk_mul_f32 v[28:29], v[2:3], v[36:37]
	v_pk_mul_f32 v[26:27], v[0:1], v[46:47]
	v_pk_mul_f32 v[32:33], v[14:15], v[50:51]
	v_pk_mul_f32 v[30:31], v[12:13], v[48:49]
	v_pk_mul_f32 v[36:37], v[10:11], v[34:35]
	v_pk_mul_f32 v[34:35], v[8:9], v[56:57]
	flat_store_dwordx4 v[20:21], v[22:25] nt
	flat_store_dwordx4 v[20:21], v[26:29] offset:16 nt
	flat_store_dwordx4 v[20:21], v[30:33] offset:2048 nt
	flat_store_dwordx4 v[20:21], v[34:37] offset:2064 nt
	s_cbranch_scc1 .LBB0_761
